# GEMM MFMA blocks: the back-to-back s_setprio 0 / s_setprio 1 between the two 16-MFMA groups removed (32 sites; net priority unchanged)
# baseline (speedup 1.0000x reference)
; #define PG8_STAGE(bufoff, gbase, voff) do { _Pragma("unroll") for (int _i = 0; _i < 2; ++_i) \
;         __builtin_amdgcn_global_load_lds((const unsigned*)((const char*)(gbase) + (voff)[_i]), (PG8_LAS unsigned*)(lds + (bufoff) + ldsw + _i * 8192), 16, 0, 0); } while (0)
; #define PG8_LDA(dst, b, h) do { _Pragma("unroll") for (int m = 0; m < 4; ++m) _Pragma("unroll") for (int k = 0; k < 2; ++k) dst[m][k] = *(const PG8_LAS bf16x8*)(lds + PG8_SA(b, h) + aoff + m * 2048 + k * 1024); } while (0)
; #define PG8_LDB(dst, b, h) do { _Pragma("unroll") for (int n = 0; n < 2; ++n) _Pragma("unroll") for (int k = 0; k < 2; ++k) dst[n][k] = *(const PG8_LAS bf16x8*)(lds + PG8_SB(b, h) + boff + n * 2048 + k * 1024); } while (0)
; #define PG8_MMA(ai, bj, At, Bt) do { __builtin_amdgcn_s_setprio(1); _Pragma("unroll") for (int m = 0; m < 4; ++m) _Pragma("unroll") for (int n = 0; n < 2; ++n) _Pragma("unroll") for (int k = 0; k < 2; ++k) \
;         acc[ai][bj][m][n] = __builtin_amdgcn_mfma_f32_16x16x32_bf16(Bt[n][k], At[m][k], acc[ai][bj][m][n], 0, 0, 0); __builtin_amdgcn_s_setprio(0); } while (0)
; #define PG8_WAIT_V(n) asm volatile("s_waitcnt vmcnt(" #n ")" ::: "memory")
; #define PG8_WAIT_L(n) asm volatile("s_waitcnt lgkmcnt(" #n ")" ::: "memory")
; #define PG8_BAR __builtin_amdgcn_s_barrier()
; #define PG8_SCHED __builtin_amdgcn_sched_barrier(0)
; template <class Epi, class Sched, bool ALIGN_EPI = false, bool SP2 = false>
; __device__ __forceinline__ void gemm_phase(PG8_LAS unsigned char* lds, const Gemm g, const Sched& S, const Epi& E, const int tid) {
;     ...
;             PG8_LDB(B0, 0, 0); PG8_LDB(B1, 0, 1); PG8_SCHED; PG8_LDA(At, 0, 0); PG8_STAGE(PG8_SA(1, 1), a1 + hstep, voffA);
;             PG8_WAIT_V(8); PG8_WAIT_L(0); PG8_BAR; PG8_MMA(0, 0, At, B0); PG8_MMA(0, 1, At, B1); PG8_BAR; PG8_SCHED;
;             PG8_LDA(At, 0, 1); PG8_STAGE(PG8_SB(0, 0), b2, voffB); PG8_STAGE(PG8_SB(0, 1), b2 + hstep, voffB); PG8_STAGE(PG8_SA(0, 0), a2, voffA);
;             PG8_WAIT_V(8); PG8_WAIT_L(0); PG8_BAR; PG8_MMA(1, 0, At, B0); PG8_MMA(1, 1, At, B1); PG8_BAR; PG8_SCHED;
.LBB0_226:
	ds_read_b128 v[144:147], v151
	ds_read_b128 v[154:157], v151 offset:1024
	ds_read_b128 v[158:161], v151 offset:2048
	ds_read_b128 v[162:165], v151 offset:3072
	ds_read_b128 v[166:169], v152
	ds_read_b128 v[170:173], v152 offset:1024
	ds_read_b128 v[174:177], v152 offset:2048
	ds_read_b128 v[178:181], v152 offset:3072
	s_add_u32 s48, s46, 0xfffc0080
	s_addc_u32 s49, s47, -1
	s_cmp_eq_u32 s79, 12
	s_cselect_b32 s51, s33, s49
	s_cselect_b32 s50, s37, s48
	s_cselect_b32 s49, s35, s78
	s_cselect_b32 s48, s43, s77
	s_add_i32 m0, s58, 0xc000
	ds_read_b128 v[182:185], v153
	ds_read_b128 v[186:189], v153 offset:1024
	ds_read_b128 v[190:193], v153 offset:2048
	ds_read_b128 v[194:197], v153 offset:3072
	ds_read_b128 v[198:201], v153 offset:4096
	ds_read_b128 v[202:205], v153 offset:5120
	ds_read_b128 v[206:209], v153 offset:6144
	ds_read_b128 v[210:213], v153 offset:7168
	global_load_lds_dwordx4 v136, s[46:47]
	s_add_i32 m0, s58, 0xe000
	s_nop 0
	global_load_lds_dwordx4 v138, s[46:47]
	s_waitcnt vmcnt(8)
	s_waitcnt lgkmcnt(0)
	s_barrier
	s_setprio 1
	s_waitcnt lgkmcnt(0)
	v_mfma_f32_16x16x32_bf16 v[124:127], v[144:147], v[182:185], v[124:127]
	v_mfma_f32_16x16x32_bf16 v[120:123], v[158:161], v[182:185], v[120:123]
	v_mfma_f32_16x16x32_bf16 v[116:119], v[144:147], v[190:193], v[116:119]
	v_mfma_f32_16x16x32_bf16 v[108:111], v[158:161], v[190:193], v[108:111]
	v_mfma_f32_16x16x32_bf16 v[100:103], v[144:147], v[198:201], v[100:103]
	v_mfma_f32_16x16x32_bf16 v[92:95], v[158:161], v[198:201], v[92:95]
	v_mfma_f32_16x16x32_bf16 v[84:87], v[144:147], v[206:209], v[84:87]
	v_mfma_f32_16x16x32_bf16 v[76:79], v[158:161], v[206:209], v[76:79]
	v_mfma_f32_16x16x32_bf16 v[124:127], v[154:157], v[186:189], v[124:127]
	v_mfma_f32_16x16x32_bf16 v[120:123], v[162:165], v[186:189], v[120:123]
	v_mfma_f32_16x16x32_bf16 v[116:119], v[154:157], v[194:197], v[116:119]
	v_mfma_f32_16x16x32_bf16 v[108:111], v[162:165], v[194:197], v[108:111]
	v_mfma_f32_16x16x32_bf16 v[100:103], v[154:157], v[202:205], v[100:103]
	v_mfma_f32_16x16x32_bf16 v[92:95], v[162:165], v[202:205], v[92:95]
	v_mfma_f32_16x16x32_bf16 v[84:87], v[154:157], v[210:213], v[84:87]
	v_mfma_f32_16x16x32_bf16 v[76:79], v[162:165], v[210:213], v[76:79]
	v_mfma_f32_16x16x32_bf16 v[112:115], v[166:169], v[182:185], v[112:115]
	v_mfma_f32_16x16x32_bf16 v[104:107], v[174:177], v[182:185], v[104:107]
	v_mfma_f32_16x16x32_bf16 v[96:99], v[166:169], v[190:193], v[96:99]
	v_mfma_f32_16x16x32_bf16 v[88:91], v[174:177], v[190:193], v[88:91]
	v_mfma_f32_16x16x32_bf16 v[80:83], v[166:169], v[198:201], v[80:83]
	v_mfma_f32_16x16x32_bf16 v[72:75], v[174:177], v[198:201], v[72:75]
	v_mfma_f32_16x16x32_bf16 v[68:71], v[166:169], v[206:209], v[68:71]
	v_mfma_f32_16x16x32_bf16 v[64:67], v[174:177], v[206:209], v[64:67]
	v_mfma_f32_16x16x32_bf16 v[112:115], v[170:173], v[186:189], v[112:115]
	v_mfma_f32_16x16x32_bf16 v[104:107], v[178:181], v[186:189], v[104:107]
	v_mfma_f32_16x16x32_bf16 v[96:99], v[170:173], v[194:197], v[96:99]
	v_mfma_f32_16x16x32_bf16 v[88:91], v[178:181], v[194:197], v[88:91]
	v_mfma_f32_16x16x32_bf16 v[80:83], v[170:173], v[202:205], v[80:83]
	v_mfma_f32_16x16x32_bf16 v[72:75], v[178:181], v[202:205], v[72:75]
	v_mfma_f32_16x16x32_bf16 v[68:71], v[170:173], v[210:213], v[68:71]
	v_mfma_f32_16x16x32_bf16 v[64:67], v[178:181], v[210:213], v[64:67]
	s_setprio 0
	s_barrier
	s_add_i32 s80, s66, s57
	v_lshl_add_u64 v[214:215], s[48:49], 0, v[130:131]
	s_mov_b32 m0, s80
	ds_read_b128 v[182:185], v153 offset:16384
	ds_read_b128 v[186:189], v153 offset:17408
	ds_read_b128 v[190:193], v153 offset:18432
	ds_read_b128 v[194:197], v153 offset:19456
	ds_read_b128 v[198:201], v153 offset:20480
	ds_read_b128 v[202:205], v153 offset:21504
	ds_read_b128 v[206:209], v153 offset:22528
	ds_read_b128 v[210:213], v153 offset:23552
	global_load_lds_dwordx4 v[214:215], off
	s_add_i32 m0, s80, 0x2000
	s_add_u32 s80, s48, 0x40000
	v_lshl_add_u64 v[216:217], s[48:49], 0, v[134:135]
	s_addc_u32 s81, s49, 0
	s_add_i32 s82, s67, s57
	global_load_lds_dwordx4 v[216:217], off
	s_mov_b32 m0, s82
	v_lshl_add_u64 v[220:221], s[50:51], 0, v[132:133]
	global_load_lds_dwordx4 v130, s[80:81]
	s_add_i32 m0, s82, 0x2000
	s_nop 0
	global_load_lds_dwordx4 v134, s[80:81]
	v_lshl_add_u64 v[218:219], s[50:51], 0, v[128:129]
	s_mov_b32 m0, s58
	s_nop 0
	global_load_lds_dwordx4 v[218:219], off
	s_mov_b32 m0, s59
	s_nop 0
	global_load_lds_dwordx4 v[220:221], off
	s_waitcnt vmcnt(8)
	s_waitcnt lgkmcnt(0)
	s_barrier
	s_setprio 1
	s_waitcnt lgkmcnt(0)
	v_mfma_f32_16x16x32_bf16 v[60:63], v[144:147], v[182:185], v[60:63]
	v_mfma_f32_16x16x32_bf16 v[56:59], v[158:161], v[182:185], v[56:59]
	v_mfma_f32_16x16x32_bf16 v[52:55], v[144:147], v[190:193], v[52:55]
	v_mfma_f32_16x16x32_bf16 v[44:47], v[158:161], v[190:193], v[44:47]
	v_mfma_f32_16x16x32_bf16 v[36:39], v[144:147], v[198:201], v[36:39]
	v_mfma_f32_16x16x32_bf16 v[28:31], v[158:161], v[198:201], v[28:31]
	v_mfma_f32_16x16x32_bf16 v[20:23], v[144:147], v[206:209], v[20:23]
	v_mfma_f32_16x16x32_bf16 v[12:15], v[158:161], v[206:209], v[12:15]
	v_mfma_f32_16x16x32_bf16 v[60:63], v[154:157], v[186:189], v[60:63]
	v_mfma_f32_16x16x32_bf16 v[56:59], v[162:165], v[186:189], v[56:59]
	v_mfma_f32_16x16x32_bf16 v[52:55], v[154:157], v[194:197], v[52:55]
	v_mfma_f32_16x16x32_bf16 v[44:47], v[162:165], v[194:197], v[44:47]
	v_mfma_f32_16x16x32_bf16 v[36:39], v[154:157], v[202:205], v[36:39]
	v_mfma_f32_16x16x32_bf16 v[28:31], v[162:165], v[202:205], v[28:31]
	v_mfma_f32_16x16x32_bf16 v[20:23], v[154:157], v[210:213], v[20:23]
	v_mfma_f32_16x16x32_bf16 v[12:15], v[162:165], v[210:213], v[12:15]
	v_mfma_f32_16x16x32_bf16 v[48:51], v[166:169], v[182:185], v[48:51]
	v_mfma_f32_16x16x32_bf16 v[40:43], v[174:177], v[182:185], v[40:43]
	v_mfma_f32_16x16x32_bf16 v[32:35], v[166:169], v[190:193], v[32:35]
	v_mfma_f32_16x16x32_bf16 v[24:27], v[174:177], v[190:193], v[24:27]
	v_mfma_f32_16x16x32_bf16 v[16:19], v[166:169], v[198:201], v[16:19]
	v_mfma_f32_16x16x32_bf16 v[8:11], v[174:177], v[198:201], v[8:11]
	v_mfma_f32_16x16x32_bf16 v[4:7], v[166:169], v[206:209], v[4:7]
	v_mfma_f32_16x16x32_bf16 v[0:3], v[174:177], v[206:209], v[0:3]
	v_mfma_f32_16x16x32_bf16 v[48:51], v[170:173], v[186:189], v[48:51]
	v_mfma_f32_16x16x32_bf16 v[40:43], v[178:181], v[186:189], v[40:43]
	v_mfma_f32_16x16x32_bf16 v[32:35], v[170:173], v[194:197], v[32:35]
	v_mfma_f32_16x16x32_bf16 v[24:27], v[178:181], v[194:197], v[24:27]
	v_mfma_f32_16x16x32_bf16 v[16:19], v[170:173], v[202:205], v[16:19]
	v_mfma_f32_16x16x32_bf16 v[8:11], v[178:181], v[202:205], v[8:11]
	v_mfma_f32_16x16x32_bf16 v[4:7], v[170:173], v[210:213], v[4:7]
	v_mfma_f32_16x16x32_bf16 v[0:3], v[178:181], v[210:213], v[0:3]
	s_setprio 0
	s_barrier
; #define PG8_STAGE(bufoff, gbase, voff) do { _Pragma("unroll") for (int _i = 0; _i < 2; ++_i) \
;         __builtin_amdgcn_global_load_lds((const unsigned*)((const char*)(gbase) + (voff)[_i]), (PG8_LAS unsigned*)(lds + (bufoff) + ldsw + _i * 8192), 16, 0, 0); } while (0)
; #define PG8_LDA(dst, b, h) do { _Pragma("unroll") for (int m = 0; m < 4; ++m) _Pragma("unroll") for (int k = 0; k < 2; ++k) dst[m][k] = *(const PG8_LAS bf16x8*)(lds + PG8_SA(b, h) + aoff + m * 2048 + k * 1024); } while (0)
; #define PG8_LDB(dst, b, h) do { _Pragma("unroll") for (int n = 0; n < 2; ++n) _Pragma("unroll") for (int k = 0; k < 2; ++k) dst[n][k] = *(const PG8_LAS bf16x8*)(lds + PG8_SB(b, h) + boff + n * 2048 + k * 1024); } while (0)
; #define PG8_MMA(ai, bj, At, Bt) do { __builtin_amdgcn_s_setprio(1); _Pragma("unroll") for (int m = 0; m < 4; ++m) _Pragma("unroll") for (int n = 0; n < 2; ++n) _Pragma("unroll") for (int k = 0; k < 2; ++k) \
;         acc[ai][bj][m][n] = __builtin_amdgcn_mfma_f32_16x16x32_bf16(Bt[n][k], At[m][k], acc[ai][bj][m][n], 0, 0, 0); __builtin_amdgcn_s_setprio(0); } while (0)
; #define PG8_WAIT_V(n) asm volatile("s_waitcnt vmcnt(" #n ")" ::: "memory")
; #define PG8_WAIT_L(n) asm volatile("s_waitcnt lgkmcnt(" #n ")" ::: "memory")
; #define PG8_BAR __builtin_amdgcn_s_barrier()
; #define PG8_SCHED __builtin_amdgcn_sched_barrier(0)
; template <class Epi, class Sched, bool ALIGN_EPI = false, bool SP2 = false>
; __device__ __forceinline__ void gemm_phase(PG8_LAS unsigned char* lds, const Gemm g, const Sched& S, const Epi& E, const int tid) {
;     ...
;             PG8_LDB(B0, 1, 0); PG8_LDB(B1, 1, 1); PG8_SCHED; PG8_LDA(At, 1, 0); PG8_STAGE(PG8_SA(0, 1), a2 + hstep, voffA);
;             PG8_WAIT_V(8); PG8_WAIT_L(0); PG8_BAR; PG8_MMA(0, 0, At, B0); PG8_MMA(0, 1, At, B1); PG8_BAR; PG8_SCHED;
	s_add_i32 s80, 0, 0x18000
	s_add_i32 s81, 0, 0x1c000
	v_add_u32_e32 v162, s80, v149
	v_add_u32_e32 v178, s81, v149
	ds_read_b128 v[144:147], v162
	ds_read_b128 v[154:157], v162 offset:1024
	ds_read_b128 v[158:161], v162 offset:2048
	ds_read_b128 v[162:165], v162 offset:3072
	ds_read_b128 v[166:169], v178
	ds_read_b128 v[170:173], v178 offset:1024
	ds_read_b128 v[174:177], v178 offset:2048
	ds_read_b128 v[178:181], v178 offset:3072
	s_add_u32 s50, s50, 0x40000
	s_addc_u32 s51, s51, 0
	s_mov_b32 m0, s60
	ds_read_b128 v[182:185], v153 offset:32768
	ds_read_b128 v[186:189], v153 offset:33792
	ds_read_b128 v[190:193], v153 offset:34816
	ds_read_b128 v[194:197], v153 offset:35840
	ds_read_b128 v[198:201], v153 offset:36864
	ds_read_b128 v[202:205], v153 offset:37888
	ds_read_b128 v[206:209], v153 offset:38912
	ds_read_b128 v[210:213], v153 offset:39936
	global_load_lds_dwordx4 v128, s[50:51]
	v_lshl_add_u64 v[222:223], s[50:51], 0, v[132:133]
	s_mov_b32 m0, s61
	s_nop 0
	global_load_lds_dwordx4 v[222:223], off
	s_waitcnt vmcnt(8)
	s_waitcnt lgkmcnt(0)
	s_barrier
	s_setprio 1
	s_waitcnt lgkmcnt(0)
	v_mfma_f32_16x16x32_bf16 v[124:127], v[144:147], v[182:185], v[124:127]
	v_mfma_f32_16x16x32_bf16 v[120:123], v[158:161], v[182:185], v[120:123]
	v_mfma_f32_16x16x32_bf16 v[116:119], v[144:147], v[190:193], v[116:119]
	v_mfma_f32_16x16x32_bf16 v[108:111], v[158:161], v[190:193], v[108:111]
	v_mfma_f32_16x16x32_bf16 v[100:103], v[144:147], v[198:201], v[100:103]
	v_mfma_f32_16x16x32_bf16 v[92:95], v[158:161], v[198:201], v[92:95]
	v_mfma_f32_16x16x32_bf16 v[84:87], v[144:147], v[206:209], v[84:87]
	v_mfma_f32_16x16x32_bf16 v[76:79], v[158:161], v[206:209], v[76:79]
	v_mfma_f32_16x16x32_bf16 v[124:127], v[154:157], v[186:189], v[124:127]
	v_mfma_f32_16x16x32_bf16 v[120:123], v[162:165], v[186:189], v[120:123]
	v_mfma_f32_16x16x32_bf16 v[116:119], v[154:157], v[194:197], v[116:119]
	v_mfma_f32_16x16x32_bf16 v[108:111], v[162:165], v[194:197], v[108:111]
	v_mfma_f32_16x16x32_bf16 v[100:103], v[154:157], v[202:205], v[100:103]
	v_mfma_f32_16x16x32_bf16 v[92:95], v[162:165], v[202:205], v[92:95]
	v_mfma_f32_16x16x32_bf16 v[84:87], v[154:157], v[210:213], v[84:87]
	v_mfma_f32_16x16x32_bf16 v[76:79], v[162:165], v[210:213], v[76:79]
	v_mfma_f32_16x16x32_bf16 v[112:115], v[166:169], v[182:185], v[112:115]
	v_mfma_f32_16x16x32_bf16 v[104:107], v[174:177], v[182:185], v[104:107]
	v_mfma_f32_16x16x32_bf16 v[96:99], v[166:169], v[190:193], v[96:99]
	v_mfma_f32_16x16x32_bf16 v[88:91], v[174:177], v[190:193], v[88:91]
	v_mfma_f32_16x16x32_bf16 v[80:83], v[166:169], v[198:201], v[80:83]
	v_mfma_f32_16x16x32_bf16 v[72:75], v[174:177], v[198:201], v[72:75]
	v_mfma_f32_16x16x32_bf16 v[68:71], v[166:169], v[206:209], v[68:71]
	v_mfma_f32_16x16x32_bf16 v[64:67], v[174:177], v[206:209], v[64:67]
	v_mfma_f32_16x16x32_bf16 v[112:115], v[170:173], v[186:189], v[112:115]
	v_mfma_f32_16x16x32_bf16 v[104:107], v[178:181], v[186:189], v[104:107]
	v_mfma_f32_16x16x32_bf16 v[96:99], v[170:173], v[194:197], v[96:99]
	v_mfma_f32_16x16x32_bf16 v[88:91], v[178:181], v[194:197], v[88:91]
	v_mfma_f32_16x16x32_bf16 v[80:83], v[170:173], v[202:205], v[80:83]
	v_mfma_f32_16x16x32_bf16 v[72:75], v[178:181], v[202:205], v[72:75]
	v_mfma_f32_16x16x32_bf16 v[68:71], v[170:173], v[210:213], v[68:71]
	v_mfma_f32_16x16x32_bf16 v[64:67], v[178:181], v[210:213], v[64:67]
	s_setprio 0
	s_barrier
; #define PG8_STAGE(bufoff, gbase, voff) do { _Pragma("unroll") for (int _i = 0; _i < 2; ++_i) \
;         __builtin_amdgcn_global_load_lds((const unsigned*)((const char*)(gbase) + (voff)[_i]), (PG8_LAS unsigned*)(lds + (bufoff) + ldsw + _i * 8192), 16, 0, 0); } while (0)
; #define PG8_LDA(dst, b, h) do { _Pragma("unroll") for (int m = 0; m < 4; ++m) _Pragma("unroll") for (int k = 0; k < 2; ++k) dst[m][k] = *(const PG8_LAS bf16x8*)(lds + PG8_SA(b, h) + aoff + m * 2048 + k * 1024); } while (0)
; #define PG8_MMA(ai, bj, At, Bt) do { __builtin_amdgcn_s_setprio(1); _Pragma("unroll") for (int m = 0; m < 4; ++m) _Pragma("unroll") for (int n = 0; n < 2; ++n) _Pragma("unroll") for (int k = 0; k < 2; ++k) \
;         acc[ai][bj][m][n] = __builtin_amdgcn_mfma_f32_16x16x32_bf16(Bt[n][k], At[m][k], acc[ai][bj][m][n], 0, 0, 0); __builtin_amdgcn_s_setprio(0); } while (0)
; #define PG8_WAIT_V(n) asm volatile("s_waitcnt vmcnt(" #n ")" ::: "memory")
; #define PG8_WAIT_L(n) asm volatile("s_waitcnt lgkmcnt(" #n ")" ::: "memory")
; #define PG8_BAR __builtin_amdgcn_s_barrier()
; #define PG8_SCHED __builtin_amdgcn_sched_barrier(0)
; template <class Epi, class Sched, bool ALIGN_EPI = false, bool SP2 = false>
; __device__ __forceinline__ void gemm_phase(PG8_LAS unsigned char* lds, const Gemm g, const Sched& S, const Epi& E, const int tid) {
;     ...
;             PG8_LDA(At, 1, 1); PG8_STAGE(PG8_SB(1, 0), b3, voffB); PG8_STAGE(PG8_SB(1, 1), b3 + hstep, voffB); PG8_STAGE(PG8_SA(1, 0), a3, voffA);
;             PG8_WAIT_V(8); PG8_WAIT_L(0); PG8_BAR; PG8_MMA(1, 0, At, B0); PG8_MMA(1, 1, At, B1); PG8_BAR; PG8_SCHED;
	s_add_i32 s50, s80, s57
	v_lshl_add_u64 v[214:215], v[214:215], 0, s[12:13]
	s_mov_b32 m0, s50
	ds_read_b128 v[182:185], v153 offset:49152
	ds_read_b128 v[186:189], v153 offset:50176
	ds_read_b128 v[190:193], v153 offset:51200
	ds_read_b128 v[194:197], v153 offset:52224
	ds_read_b128 v[198:201], v153 offset:53248
	ds_read_b128 v[202:205], v153 offset:54272
	ds_read_b128 v[206:209], v153 offset:55296
	ds_read_b128 v[210:213], v153 offset:56320
	global_load_lds_dwordx4 v[214:215], off
	s_add_i32 m0, s50, 0x2000
	s_add_u32 s48, s48, 0x40080
	v_lshl_add_u64 v[214:215], v[216:217], 0, s[12:13]
	s_addc_u32 s49, s49, 0
	s_add_i32 s50, s81, s57
	global_load_lds_dwordx4 v[214:215], off
	s_mov_b32 m0, s50
	s_nop 0
	global_load_lds_dwordx4 v130, s[48:49]
	s_add_i32 m0, s50, 0x2000
	s_nop 0
	global_load_lds_dwordx4 v134, s[48:49]
	v_lshl_add_u64 v[214:215], v[218:219], 0, s[12:13]
	s_mov_b32 m0, s63
	s_nop 0
	global_load_lds_dwordx4 v[214:215], off
	v_lshl_add_u64 v[214:215], v[220:221], 0, s[12:13]
	s_mov_b32 m0, s64
	s_nop 0
	global_load_lds_dwordx4 v[214:215], off
	s_waitcnt vmcnt(8)
	s_waitcnt lgkmcnt(0)
	s_barrier
	s_setprio 1
	s_waitcnt lgkmcnt(0)
	v_mfma_f32_16x16x32_bf16 v[60:63], v[144:147], v[182:185], v[60:63]
	v_mfma_f32_16x16x32_bf16 v[56:59], v[158:161], v[182:185], v[56:59]
	v_mfma_f32_16x16x32_bf16 v[52:55], v[144:147], v[190:193], v[52:55]
	v_mfma_f32_16x16x32_bf16 v[44:47], v[158:161], v[190:193], v[44:47]
	v_mfma_f32_16x16x32_bf16 v[36:39], v[144:147], v[198:201], v[36:39]
	v_mfma_f32_16x16x32_bf16 v[28:31], v[158:161], v[198:201], v[28:31]
	v_mfma_f32_16x16x32_bf16 v[20:23], v[144:147], v[206:209], v[20:23]
	v_mfma_f32_16x16x32_bf16 v[12:15], v[158:161], v[206:209], v[12:15]
	v_mfma_f32_16x16x32_bf16 v[60:63], v[154:157], v[186:189], v[60:63]
	v_mfma_f32_16x16x32_bf16 v[56:59], v[162:165], v[186:189], v[56:59]
	v_mfma_f32_16x16x32_bf16 v[52:55], v[154:157], v[194:197], v[52:55]
	v_mfma_f32_16x16x32_bf16 v[44:47], v[162:165], v[194:197], v[44:47]
	v_mfma_f32_16x16x32_bf16 v[36:39], v[154:157], v[202:205], v[36:39]
	v_mfma_f32_16x16x32_bf16 v[28:31], v[162:165], v[202:205], v[28:31]
	v_mfma_f32_16x16x32_bf16 v[20:23], v[154:157], v[210:213], v[20:23]
	v_mfma_f32_16x16x32_bf16 v[12:15], v[162:165], v[210:213], v[12:15]
	v_mfma_f32_16x16x32_bf16 v[48:51], v[166:169], v[182:185], v[48:51]
	v_mfma_f32_16x16x32_bf16 v[40:43], v[174:177], v[182:185], v[40:43]
	v_mfma_f32_16x16x32_bf16 v[32:35], v[166:169], v[190:193], v[32:35]
	v_mfma_f32_16x16x32_bf16 v[24:27], v[174:177], v[190:193], v[24:27]
	v_mfma_f32_16x16x32_bf16 v[16:19], v[166:169], v[198:201], v[16:19]
	v_mfma_f32_16x16x32_bf16 v[8:11], v[174:177], v[198:201], v[8:11]
	v_mfma_f32_16x16x32_bf16 v[4:7], v[166:169], v[206:209], v[4:7]
	v_mfma_f32_16x16x32_bf16 v[0:3], v[174:177], v[206:209], v[0:3]
	v_mfma_f32_16x16x32_bf16 v[48:51], v[170:173], v[186:189], v[48:51]
	v_mfma_f32_16x16x32_bf16 v[40:43], v[178:181], v[186:189], v[40:43]
	v_mfma_f32_16x16x32_bf16 v[32:35], v[170:173], v[194:197], v[32:35]
	v_mfma_f32_16x16x32_bf16 v[24:27], v[178:181], v[194:197], v[24:27]
	v_mfma_f32_16x16x32_bf16 v[16:19], v[170:173], v[202:205], v[16:19]
	v_mfma_f32_16x16x32_bf16 v[8:11], v[178:181], v[202:205], v[8:11]
	v_mfma_f32_16x16x32_bf16 v[4:7], v[170:173], v[210:213], v[4:7]
	v_mfma_f32_16x16x32_bf16 v[0:3], v[178:181], v[210:213], v[0:3]
	s_setprio 0
	s_barrier
	s_add_i32 s79, s79, 2
	s_add_u32 s46, s46, 0x100
	s_addc_u32 s47, s47, 0
	s_add_u32 s77, s77, 0x100
	s_addc_u32 s78, s78, 0
	s_cmp_gt_u32 s79, 13
	s_cbranch_scc0 .LBB0_226
	s_and_b64 vcc, exec, s[14:15]
	s_cbranch_vccz .LBB0_231
	s_barrier
	v_lshl_add_u32 v146, s42, 8, v148
	s_cmp_gt_i32 s76, 7
	s_mov_b64 s[42:43], -1
	s_cbranch_scc1 .LBB0_232

; #define PG8_STAGE(bufoff, gbase, voff) do { _Pragma("unroll") for (int _i = 0; _i < 2; ++_i) \
;         __builtin_amdgcn_global_load_lds((const unsigned*)((const char*)(gbase) + (voff)[_i]), (PG8_LAS unsigned*)(lds + (bufoff) + ldsw + _i * 8192), 16, 0, 0); } while (0)
; #define PG8_LDA(dst, b, h) do { _Pragma("unroll") for (int m = 0; m < 4; ++m) _Pragma("unroll") for (int k = 0; k < 2; ++k) dst[m][k] = *(const PG8_LAS bf16x8*)(lds + PG8_SA(b, h) + aoff + m * 2048 + k * 1024); } while (0)
; #define PG8_LDB(dst, b, h) do { _Pragma("unroll") for (int n = 0; n < 2; ++n) _Pragma("unroll") for (int k = 0; k < 2; ++k) dst[n][k] = *(const PG8_LAS bf16x8*)(lds + PG8_SB(b, h) + boff + n * 2048 + k * 1024); } while (0)
; #define PG8_MMA(ai, bj, At, Bt) do { __builtin_amdgcn_s_setprio(1); _Pragma("unroll") for (int m = 0; m < 4; ++m) _Pragma("unroll") for (int n = 0; n < 2; ++n) _Pragma("unroll") for (int k = 0; k < 2; ++k) \
;         acc[ai][bj][m][n] = __builtin_amdgcn_mfma_f32_16x16x32_bf16(Bt[n][k], At[m][k], acc[ai][bj][m][n], 0, 0, 0); __builtin_amdgcn_s_setprio(0); } while (0)
; #define PG8_WAIT_V(n) asm volatile("s_waitcnt vmcnt(" #n ")" ::: "memory")
; #define PG8_WAIT_L(n) asm volatile("s_waitcnt lgkmcnt(" #n ")" ::: "memory")
; #define PG8_BAR __builtin_amdgcn_s_barrier()
; #define PG8_SCHED __builtin_amdgcn_sched_barrier(0)
; template <class Epi, class Sched, bool ALIGN_EPI = false, bool SP2 = false>
; __device__ __forceinline__ void gemm_phase(PG8_LAS unsigned char* lds, const Gemm g, const Sched& S, const Epi& E, const int tid) {
;     ...
;             PG8_LDB(B0, 0, 0); PG8_LDB(B1, 0, 1); PG8_SCHED; PG8_LDA(At, 0, 0); PG8_STAGE(PG8_SA(1, 1), a1 + hstep, voffA);
;             PG8_WAIT_V(8); PG8_WAIT_L(0); PG8_BAR; PG8_MMA(0, 0, At, B0); PG8_MMA(0, 1, At, B1); PG8_BAR; PG8_SCHED;
;             PG8_LDA(At, 0, 1); PG8_STAGE(PG8_SB(0, 0), b2, voffB); PG8_STAGE(PG8_SB(0, 1), b2 + hstep, voffB); PG8_STAGE(PG8_SA(0, 0), a2, voffA);
;             PG8_WAIT_V(8); PG8_WAIT_L(0); PG8_BAR; PG8_MMA(1, 0, At, B0); PG8_MMA(1, 1, At, B1); PG8_BAR; PG8_SCHED;
.LBB0_674:
	ds_read_b128 v[128:131], v180
	ds_read_b128 v[132:135], v180 offset:1024
	ds_read_b128 v[136:139], v180 offset:2048
	ds_read_b128 v[140:143], v180 offset:3072
	ds_read_b128 v[184:187], v181
	ds_read_b128 v[188:191], v181 offset:1024
	ds_read_b128 v[192:195], v181 offset:2048
	ds_read_b128 v[196:199], v181 offset:3072
	s_add_u32 s26, s24, 0xfffc0080
	s_addc_u32 s27, s25, -1
	s_cmp_eq_u32 s61, 12
	s_cselect_b32 s29, s23, s27
	s_cselect_b32 s28, s30, s26
	s_cselect_b32 s27, s17, s60
	s_cselect_b32 s26, s31, s33
	s_add_i32 m0, s44, 0xc000
	ds_read_b128 v[200:203], v182
	ds_read_b128 v[204:207], v182 offset:1024
	ds_read_b128 v[208:211], v182 offset:2048
	ds_read_b128 v[212:215], v182 offset:3072
	ds_read_b128 v[216:219], v182 offset:4096
	ds_read_b128 v[220:223], v182 offset:5120
	ds_read_b128 v[224:227], v182 offset:6144
	ds_read_b128 v[228:231], v182 offset:7168
	global_load_lds_dwordx4 v168, s[24:25]
	s_add_i32 m0, s44, 0xe000
	s_nop 0
	global_load_lds_dwordx4 v170, s[24:25]
	s_waitcnt vmcnt(8)
	s_waitcnt lgkmcnt(0)
	s_barrier
	s_setprio 1
	s_waitcnt lgkmcnt(0)
	v_mfma_f32_16x16x32_bf16 v[124:127], v[128:131], v[200:203], v[124:127]
	v_mfma_f32_16x16x32_bf16 v[120:123], v[136:139], v[200:203], v[120:123]
	v_mfma_f32_16x16x32_bf16 v[116:119], v[128:131], v[208:211], v[116:119]
	v_mfma_f32_16x16x32_bf16 v[108:111], v[136:139], v[208:211], v[108:111]
	v_mfma_f32_16x16x32_bf16 v[100:103], v[128:131], v[216:219], v[100:103]
	v_mfma_f32_16x16x32_bf16 v[92:95], v[136:139], v[216:219], v[92:95]
	v_mfma_f32_16x16x32_bf16 v[84:87], v[128:131], v[224:227], v[84:87]
	v_mfma_f32_16x16x32_bf16 v[76:79], v[136:139], v[224:227], v[76:79]
	v_mfma_f32_16x16x32_bf16 v[124:127], v[132:135], v[204:207], v[124:127]
	v_mfma_f32_16x16x32_bf16 v[120:123], v[140:143], v[204:207], v[120:123]
	v_mfma_f32_16x16x32_bf16 v[116:119], v[132:135], v[212:215], v[116:119]
	v_mfma_f32_16x16x32_bf16 v[108:111], v[140:143], v[212:215], v[108:111]
	v_mfma_f32_16x16x32_bf16 v[100:103], v[132:135], v[220:223], v[100:103]
	v_mfma_f32_16x16x32_bf16 v[92:95], v[140:143], v[220:223], v[92:95]
	v_mfma_f32_16x16x32_bf16 v[84:87], v[132:135], v[228:231], v[84:87]
	v_mfma_f32_16x16x32_bf16 v[76:79], v[140:143], v[228:231], v[76:79]
	v_mfma_f32_16x16x32_bf16 v[112:115], v[184:187], v[200:203], v[112:115]
	v_mfma_f32_16x16x32_bf16 v[104:107], v[192:195], v[200:203], v[104:107]
	v_mfma_f32_16x16x32_bf16 v[96:99], v[184:187], v[208:211], v[96:99]
	v_mfma_f32_16x16x32_bf16 v[88:91], v[192:195], v[208:211], v[88:91]
	v_mfma_f32_16x16x32_bf16 v[80:83], v[184:187], v[216:219], v[80:83]
	v_mfma_f32_16x16x32_bf16 v[72:75], v[192:195], v[216:219], v[72:75]
	v_mfma_f32_16x16x32_bf16 v[68:71], v[184:187], v[224:227], v[68:71]
	v_mfma_f32_16x16x32_bf16 v[64:67], v[192:195], v[224:227], v[64:67]
	v_mfma_f32_16x16x32_bf16 v[112:115], v[188:191], v[204:207], v[112:115]
	v_mfma_f32_16x16x32_bf16 v[104:107], v[196:199], v[204:207], v[104:107]
	v_mfma_f32_16x16x32_bf16 v[96:99], v[188:191], v[212:215], v[96:99]
	v_mfma_f32_16x16x32_bf16 v[88:91], v[196:199], v[212:215], v[88:91]
	v_mfma_f32_16x16x32_bf16 v[80:83], v[188:191], v[220:223], v[80:83]
	v_mfma_f32_16x16x32_bf16 v[72:75], v[196:199], v[220:223], v[72:75]
	v_mfma_f32_16x16x32_bf16 v[68:71], v[188:191], v[228:231], v[68:71]
	v_mfma_f32_16x16x32_bf16 v[64:67], v[196:199], v[228:231], v[64:67]
	s_setprio 0
	s_barrier
	s_add_i32 s62, s56, s43
	v_lshl_add_u64 v[176:177], s[26:27], 0, v[146:147]
	s_mov_b32 m0, s62
	ds_read_b128 v[200:203], v182 offset:16384
	ds_read_b128 v[204:207], v182 offset:17408
	ds_read_b128 v[208:211], v182 offset:18432
	ds_read_b128 v[212:215], v182 offset:19456
	ds_read_b128 v[216:219], v182 offset:20480
	ds_read_b128 v[220:223], v182 offset:21504
	ds_read_b128 v[224:227], v182 offset:22528
	ds_read_b128 v[228:231], v182 offset:23552
	global_load_lds_dwordx4 v[176:177], off
	s_add_i32 m0, s62, 0x2000
	s_add_u32 s62, s26, 0x40000
	v_lshl_add_u64 v[232:233], s[26:27], 0, v[150:151]
	s_addc_u32 s63, s27, 0
	s_add_i32 s64, s57, s43
	global_load_lds_dwordx4 v[232:233], off
	s_mov_b32 m0, s64
	v_lshl_add_u64 v[236:237], s[28:29], 0, v[148:149]
	global_load_lds_dwordx4 v146, s[62:63]
	s_add_i32 m0, s64, 0x2000
	s_nop 0
	global_load_lds_dwordx4 v150, s[62:63]
	v_lshl_add_u64 v[234:235], s[28:29], 0, v[144:145]
	s_mov_b32 m0, s44
	s_nop 0
	global_load_lds_dwordx4 v[234:235], off
	s_mov_b32 m0, s45
	s_nop 0
	global_load_lds_dwordx4 v[236:237], off
	s_waitcnt vmcnt(8)
	s_waitcnt lgkmcnt(0)
	s_barrier
	s_setprio 1
	s_waitcnt lgkmcnt(0)
	v_mfma_f32_16x16x32_bf16 v[60:63], v[128:131], v[200:203], v[60:63]
	v_mfma_f32_16x16x32_bf16 v[56:59], v[136:139], v[200:203], v[56:59]
	v_mfma_f32_16x16x32_bf16 v[52:55], v[128:131], v[208:211], v[52:55]
	v_mfma_f32_16x16x32_bf16 v[44:47], v[136:139], v[208:211], v[44:47]
	v_mfma_f32_16x16x32_bf16 v[36:39], v[128:131], v[216:219], v[36:39]
	v_mfma_f32_16x16x32_bf16 v[28:31], v[136:139], v[216:219], v[28:31]
	v_mfma_f32_16x16x32_bf16 v[20:23], v[128:131], v[224:227], v[20:23]
	v_mfma_f32_16x16x32_bf16 v[12:15], v[136:139], v[224:227], v[12:15]
	v_mfma_f32_16x16x32_bf16 v[60:63], v[132:135], v[204:207], v[60:63]
	v_mfma_f32_16x16x32_bf16 v[56:59], v[140:143], v[204:207], v[56:59]
	v_mfma_f32_16x16x32_bf16 v[52:55], v[132:135], v[212:215], v[52:55]
	v_mfma_f32_16x16x32_bf16 v[44:47], v[140:143], v[212:215], v[44:47]
	v_mfma_f32_16x16x32_bf16 v[36:39], v[132:135], v[220:223], v[36:39]
	v_mfma_f32_16x16x32_bf16 v[28:31], v[140:143], v[220:223], v[28:31]
	v_mfma_f32_16x16x32_bf16 v[20:23], v[132:135], v[228:231], v[20:23]
	v_mfma_f32_16x16x32_bf16 v[12:15], v[140:143], v[228:231], v[12:15]
	v_mfma_f32_16x16x32_bf16 v[48:51], v[184:187], v[200:203], v[48:51]
	v_mfma_f32_16x16x32_bf16 v[40:43], v[192:195], v[200:203], v[40:43]
	v_mfma_f32_16x16x32_bf16 v[32:35], v[184:187], v[208:211], v[32:35]
	v_mfma_f32_16x16x32_bf16 v[24:27], v[192:195], v[208:211], v[24:27]
	v_mfma_f32_16x16x32_bf16 v[16:19], v[184:187], v[216:219], v[16:19]
	v_mfma_f32_16x16x32_bf16 v[8:11], v[192:195], v[216:219], v[8:11]
	v_mfma_f32_16x16x32_bf16 v[4:7], v[184:187], v[224:227], v[4:7]
	v_mfma_f32_16x16x32_bf16 v[0:3], v[192:195], v[224:227], v[0:3]
	v_mfma_f32_16x16x32_bf16 v[48:51], v[188:191], v[204:207], v[48:51]
	v_mfma_f32_16x16x32_bf16 v[40:43], v[196:199], v[204:207], v[40:43]
	v_mfma_f32_16x16x32_bf16 v[32:35], v[188:191], v[212:215], v[32:35]
	v_mfma_f32_16x16x32_bf16 v[24:27], v[196:199], v[212:215], v[24:27]
	v_mfma_f32_16x16x32_bf16 v[16:19], v[188:191], v[220:223], v[16:19]
	v_mfma_f32_16x16x32_bf16 v[8:11], v[196:199], v[220:223], v[8:11]
	v_mfma_f32_16x16x32_bf16 v[4:7], v[188:191], v[228:231], v[4:7]
	v_mfma_f32_16x16x32_bf16 v[0:3], v[196:199], v[228:231], v[0:3]
	s_setprio 0
	s_barrier
; #define PG8_STAGE(bufoff, gbase, voff) do { _Pragma("unroll") for (int _i = 0; _i < 2; ++_i) \
;         __builtin_amdgcn_global_load_lds((const unsigned*)((const char*)(gbase) + (voff)[_i]), (PG8_LAS unsigned*)(lds + (bufoff) + ldsw + _i * 8192), 16, 0, 0); } while (0)
; #define PG8_LDA(dst, b, h) do { _Pragma("unroll") for (int m = 0; m < 4; ++m) _Pragma("unroll") for (int k = 0; k < 2; ++k) dst[m][k] = *(const PG8_LAS bf16x8*)(lds + PG8_SA(b, h) + aoff + m * 2048 + k * 1024); } while (0)
; #define PG8_LDB(dst, b, h) do { _Pragma("unroll") for (int n = 0; n < 2; ++n) _Pragma("unroll") for (int k = 0; k < 2; ++k) dst[n][k] = *(const PG8_LAS bf16x8*)(lds + PG8_SB(b, h) + boff + n * 2048 + k * 1024); } while (0)
; #define PG8_MMA(ai, bj, At, Bt) do { __builtin_amdgcn_s_setprio(1); _Pragma("unroll") for (int m = 0; m < 4; ++m) _Pragma("unroll") for (int n = 0; n < 2; ++n) _Pragma("unroll") for (int k = 0; k < 2; ++k) \
;         acc[ai][bj][m][n] = __builtin_amdgcn_mfma_f32_16x16x32_bf16(Bt[n][k], At[m][k], acc[ai][bj][m][n], 0, 0, 0); __builtin_amdgcn_s_setprio(0); } while (0)
; #define PG8_WAIT_V(n) asm volatile("s_waitcnt vmcnt(" #n ")" ::: "memory")
; #define PG8_WAIT_L(n) asm volatile("s_waitcnt lgkmcnt(" #n ")" ::: "memory")
; #define PG8_BAR __builtin_amdgcn_s_barrier()
; #define PG8_SCHED __builtin_amdgcn_sched_barrier(0)
; template <class Epi, class Sched, bool ALIGN_EPI = false, bool SP2 = false>
; __device__ __forceinline__ void gemm_phase(PG8_LAS unsigned char* lds, const Gemm g, const Sched& S, const Epi& E, const int tid) {
;     ...
;             PG8_LDB(B0, 1, 0); PG8_LDB(B1, 1, 1); PG8_SCHED; PG8_LDA(At, 1, 0); PG8_STAGE(PG8_SA(0, 1), a2 + hstep, voffA);
;             PG8_WAIT_V(8); PG8_WAIT_L(0); PG8_BAR; PG8_MMA(0, 0, At, B0); PG8_MMA(0, 1, At, B1); PG8_BAR; PG8_SCHED;
;             PG8_LDA(At, 1, 1); PG8_STAGE(PG8_SB(1, 0), b3, voffB); PG8_STAGE(PG8_SB(1, 1), b3 + hstep, voffB); PG8_STAGE(PG8_SA(1, 0), a3, voffA);
;             PG8_WAIT_V(8); PG8_WAIT_L(0); PG8_BAR; PG8_MMA(1, 0, At, B0); PG8_MMA(1, 1, At, B1); PG8_BAR; PG8_SCHED;
	s_add_i32 s62, 0, 0x18000
	s_add_i32 s63, 0, 0x1c000
	v_add_u32_e32 v140, s62, v178
	v_add_u32_e32 v183, s63, v178
	ds_read_b128 v[128:131], v140
	ds_read_b128 v[132:135], v140 offset:1024
	ds_read_b128 v[136:139], v140 offset:2048
	ds_read_b128 v[140:143], v140 offset:3072
	ds_read_b128 v[184:187], v183
	ds_read_b128 v[188:191], v183 offset:1024
	ds_read_b128 v[192:195], v183 offset:2048
	ds_read_b128 v[196:199], v183 offset:3072
	s_add_u32 s28, s28, 0x40000
	s_addc_u32 s29, s29, 0
	s_mov_b32 m0, s46
	ds_read_b128 v[200:203], v182 offset:32768
	ds_read_b128 v[204:207], v182 offset:33792
	ds_read_b128 v[208:211], v182 offset:34816
	ds_read_b128 v[212:215], v182 offset:35840
	ds_read_b128 v[216:219], v182 offset:36864
	ds_read_b128 v[220:223], v182 offset:37888
	ds_read_b128 v[224:227], v182 offset:38912
	ds_read_b128 v[228:231], v182 offset:39936
	global_load_lds_dwordx4 v144, s[28:29]
	v_lshl_add_u64 v[238:239], s[28:29], 0, v[148:149]
	s_mov_b32 m0, s47
	s_nop 0
	global_load_lds_dwordx4 v[238:239], off
	s_waitcnt vmcnt(8)
	s_waitcnt lgkmcnt(0)
	s_barrier
	s_setprio 1
	s_waitcnt lgkmcnt(0)
	v_mfma_f32_16x16x32_bf16 v[124:127], v[128:131], v[200:203], v[124:127]
	v_mfma_f32_16x16x32_bf16 v[120:123], v[136:139], v[200:203], v[120:123]
	v_mfma_f32_16x16x32_bf16 v[116:119], v[128:131], v[208:211], v[116:119]
	v_mfma_f32_16x16x32_bf16 v[108:111], v[136:139], v[208:211], v[108:111]
	v_mfma_f32_16x16x32_bf16 v[100:103], v[128:131], v[216:219], v[100:103]
	v_mfma_f32_16x16x32_bf16 v[92:95], v[136:139], v[216:219], v[92:95]
	v_mfma_f32_16x16x32_bf16 v[84:87], v[128:131], v[224:227], v[84:87]
	v_mfma_f32_16x16x32_bf16 v[76:79], v[136:139], v[224:227], v[76:79]
	v_mfma_f32_16x16x32_bf16 v[124:127], v[132:135], v[204:207], v[124:127]
	v_mfma_f32_16x16x32_bf16 v[120:123], v[140:143], v[204:207], v[120:123]
	v_mfma_f32_16x16x32_bf16 v[116:119], v[132:135], v[212:215], v[116:119]
	v_mfma_f32_16x16x32_bf16 v[108:111], v[140:143], v[212:215], v[108:111]
	v_mfma_f32_16x16x32_bf16 v[100:103], v[132:135], v[220:223], v[100:103]
	v_mfma_f32_16x16x32_bf16 v[92:95], v[140:143], v[220:223], v[92:95]
	v_mfma_f32_16x16x32_bf16 v[84:87], v[132:135], v[228:231], v[84:87]
	v_mfma_f32_16x16x32_bf16 v[76:79], v[140:143], v[228:231], v[76:79]
	v_mfma_f32_16x16x32_bf16 v[112:115], v[184:187], v[200:203], v[112:115]
	v_mfma_f32_16x16x32_bf16 v[104:107], v[192:195], v[200:203], v[104:107]
	v_mfma_f32_16x16x32_bf16 v[96:99], v[184:187], v[208:211], v[96:99]
	v_mfma_f32_16x16x32_bf16 v[88:91], v[192:195], v[208:211], v[88:91]
	v_mfma_f32_16x16x32_bf16 v[80:83], v[184:187], v[216:219], v[80:83]
	v_mfma_f32_16x16x32_bf16 v[72:75], v[192:195], v[216:219], v[72:75]
	v_mfma_f32_16x16x32_bf16 v[68:71], v[184:187], v[224:227], v[68:71]
	v_mfma_f32_16x16x32_bf16 v[64:67], v[192:195], v[224:227], v[64:67]
	v_mfma_f32_16x16x32_bf16 v[112:115], v[188:191], v[204:207], v[112:115]
	v_mfma_f32_16x16x32_bf16 v[104:107], v[196:199], v[204:207], v[104:107]
	v_mfma_f32_16x16x32_bf16 v[96:99], v[188:191], v[212:215], v[96:99]
	v_mfma_f32_16x16x32_bf16 v[88:91], v[196:199], v[212:215], v[88:91]
	v_mfma_f32_16x16x32_bf16 v[80:83], v[188:191], v[220:223], v[80:83]
	v_mfma_f32_16x16x32_bf16 v[72:75], v[196:199], v[220:223], v[72:75]
	v_mfma_f32_16x16x32_bf16 v[68:71], v[188:191], v[228:231], v[68:71]
	v_mfma_f32_16x16x32_bf16 v[64:67], v[196:199], v[228:231], v[64:67]
	s_setprio 0
	s_barrier
	s_add_i32 s28, s62, s43
	v_lshl_add_u64 v[176:177], v[176:177], 0, s[12:13]
	s_mov_b32 m0, s28
	ds_read_b128 v[200:203], v182 offset:49152
	ds_read_b128 v[204:207], v182 offset:50176
	ds_read_b128 v[208:211], v182 offset:51200
	ds_read_b128 v[212:215], v182 offset:52224
	ds_read_b128 v[216:219], v182 offset:53248
	ds_read_b128 v[220:223], v182 offset:54272
	ds_read_b128 v[224:227], v182 offset:55296
	ds_read_b128 v[228:231], v182 offset:56320
	global_load_lds_dwordx4 v[176:177], off
	s_add_i32 m0, s28, 0x2000
	s_add_u32 s26, s26, 0x40080
	v_lshl_add_u64 v[176:177], v[232:233], 0, s[12:13]
	s_addc_u32 s27, s27, 0
	s_add_i32 s28, s63, s43
	global_load_lds_dwordx4 v[176:177], off
	s_mov_b32 m0, s28
	s_nop 0
	global_load_lds_dwordx4 v146, s[26:27]
	s_add_i32 m0, s28, 0x2000
	s_nop 0
	global_load_lds_dwordx4 v150, s[26:27]
	v_lshl_add_u64 v[176:177], v[234:235], 0, s[12:13]
	s_mov_b32 m0, s53
	s_nop 0
	global_load_lds_dwordx4 v[176:177], off
	v_lshl_add_u64 v[176:177], v[236:237], 0, s[12:13]
	s_mov_b32 m0, s54
	s_nop 0
	global_load_lds_dwordx4 v[176:177], off
	s_waitcnt vmcnt(8)
	s_waitcnt lgkmcnt(0)
	s_barrier
	s_setprio 1
	s_waitcnt lgkmcnt(0)
	v_mfma_f32_16x16x32_bf16 v[60:63], v[128:131], v[200:203], v[60:63]
	v_mfma_f32_16x16x32_bf16 v[56:59], v[136:139], v[200:203], v[56:59]
	v_mfma_f32_16x16x32_bf16 v[52:55], v[128:131], v[208:211], v[52:55]
	v_mfma_f32_16x16x32_bf16 v[44:47], v[136:139], v[208:211], v[44:47]
	v_mfma_f32_16x16x32_bf16 v[36:39], v[128:131], v[216:219], v[36:39]
	v_mfma_f32_16x16x32_bf16 v[28:31], v[136:139], v[216:219], v[28:31]
	v_mfma_f32_16x16x32_bf16 v[20:23], v[128:131], v[224:227], v[20:23]
	v_mfma_f32_16x16x32_bf16 v[12:15], v[136:139], v[224:227], v[12:15]
	v_mfma_f32_16x16x32_bf16 v[60:63], v[132:135], v[204:207], v[60:63]
	v_mfma_f32_16x16x32_bf16 v[56:59], v[140:143], v[204:207], v[56:59]
	v_mfma_f32_16x16x32_bf16 v[52:55], v[132:135], v[212:215], v[52:55]
	v_mfma_f32_16x16x32_bf16 v[44:47], v[140:143], v[212:215], v[44:47]
	v_mfma_f32_16x16x32_bf16 v[36:39], v[132:135], v[220:223], v[36:39]
	v_mfma_f32_16x16x32_bf16 v[28:31], v[140:143], v[220:223], v[28:31]
	v_mfma_f32_16x16x32_bf16 v[20:23], v[132:135], v[228:231], v[20:23]
	v_mfma_f32_16x16x32_bf16 v[12:15], v[140:143], v[228:231], v[12:15]
	v_mfma_f32_16x16x32_bf16 v[48:51], v[184:187], v[200:203], v[48:51]
	v_mfma_f32_16x16x32_bf16 v[40:43], v[192:195], v[200:203], v[40:43]
	v_mfma_f32_16x16x32_bf16 v[32:35], v[184:187], v[208:211], v[32:35]
	v_mfma_f32_16x16x32_bf16 v[24:27], v[192:195], v[208:211], v[24:27]
	v_mfma_f32_16x16x32_bf16 v[16:19], v[184:187], v[216:219], v[16:19]
	v_mfma_f32_16x16x32_bf16 v[8:11], v[192:195], v[216:219], v[8:11]
	v_mfma_f32_16x16x32_bf16 v[4:7], v[184:187], v[224:227], v[4:7]
	v_mfma_f32_16x16x32_bf16 v[0:3], v[192:195], v[224:227], v[0:3]
	v_mfma_f32_16x16x32_bf16 v[48:51], v[188:191], v[204:207], v[48:51]
	v_mfma_f32_16x16x32_bf16 v[40:43], v[196:199], v[204:207], v[40:43]
	v_mfma_f32_16x16x32_bf16 v[32:35], v[188:191], v[212:215], v[32:35]
	v_mfma_f32_16x16x32_bf16 v[24:27], v[196:199], v[212:215], v[24:27]
	v_mfma_f32_16x16x32_bf16 v[16:19], v[188:191], v[220:223], v[16:19]
	v_mfma_f32_16x16x32_bf16 v[8:11], v[196:199], v[220:223], v[8:11]
	v_mfma_f32_16x16x32_bf16 v[4:7], v[188:191], v[228:231], v[4:7]
	v_mfma_f32_16x16x32_bf16 v[0:3], v[196:199], v[228:231], v[0:3]
	s_setprio 0
	s_barrier
	s_add_i32 s61, s61, 2
	s_add_u32 s24, s24, 0x100
	s_addc_u32 s25, s25, 0
	s_add_u32 s33, s33, 0x100
	s_addc_u32 s60, s60, 0
	s_cmp_gt_u32 s61, 13
	s_cbranch_scc0 .LBB0_674
	s_and_b64 vcc, exec, s[14:15]
	s_cbranch_vccz .LBB0_677
	s_barrier

; #define PG8_STAGE(bufoff, gbase, voff) do { _Pragma("unroll") for (int _i = 0; _i < 2; ++_i) \
;         __builtin_amdgcn_global_load_lds((const unsigned*)((const char*)(gbase) + (voff)[_i]), (PG8_LAS unsigned*)(lds + (bufoff) + ldsw + _i * 8192), 16, 0, 0); } while (0)
; #define PG8_LDA(dst, b, h) do { _Pragma("unroll") for (int m = 0; m < 4; ++m) _Pragma("unroll") for (int k = 0; k < 2; ++k) dst[m][k] = *(const PG8_LAS bf16x8*)(lds + PG8_SA(b, h) + aoff + m * 2048 + k * 1024); } while (0)
; #define PG8_LDB(dst, b, h) do { _Pragma("unroll") for (int n = 0; n < 2; ++n) _Pragma("unroll") for (int k = 0; k < 2; ++k) dst[n][k] = *(const PG8_LAS bf16x8*)(lds + PG8_SB(b, h) + boff + n * 2048 + k * 1024); } while (0)
; #define PG8_MMA(ai, bj, At, Bt) do { __builtin_amdgcn_s_setprio(1); _Pragma("unroll") for (int m = 0; m < 4; ++m) _Pragma("unroll") for (int n = 0; n < 2; ++n) _Pragma("unroll") for (int k = 0; k < 2; ++k) \
;         acc[ai][bj][m][n] = __builtin_amdgcn_mfma_f32_16x16x32_bf16(Bt[n][k], At[m][k], acc[ai][bj][m][n], 0, 0, 0); __builtin_amdgcn_s_setprio(0); } while (0)
; #define PG8_WAIT_V(n) asm volatile("s_waitcnt vmcnt(" #n ")" ::: "memory")
; #define PG8_WAIT_L(n) asm volatile("s_waitcnt lgkmcnt(" #n ")" ::: "memory")
; #define PG8_BAR __builtin_amdgcn_s_barrier()
; #define PG8_SCHED __builtin_amdgcn_sched_barrier(0)
; template <class Epi, class Sched, bool ALIGN_EPI = false, bool SP2 = false>
; __device__ __forceinline__ void gemm_phase(PG8_LAS unsigned char* lds, const Gemm g, const Sched& S, const Epi& E, const int tid) {
;     ...
;             PG8_LDB(B0, 0, 0); PG8_LDB(B1, 0, 1); PG8_SCHED; PG8_LDA(At, 0, 0); PG8_STAGE(PG8_SA(1, 1), a1 + hstep, voffA);
;             PG8_WAIT_V(8); PG8_WAIT_L(0); PG8_BAR; PG8_MMA(0, 0, At, B0); PG8_MMA(0, 1, At, B1); PG8_BAR; PG8_SCHED;
;             PG8_LDA(At, 0, 1); PG8_STAGE(PG8_SB(0, 0), b2, voffB); PG8_STAGE(PG8_SB(0, 1), b2 + hstep, voffB); PG8_STAGE(PG8_SA(0, 0), a2, voffA);
;             PG8_WAIT_V(8); PG8_WAIT_L(0); PG8_BAR; PG8_MMA(1, 0, At, B0); PG8_MMA(1, 1, At, B1); PG8_BAR; PG8_SCHED;
.LBB0_813:
	ds_read_b128 v[152:155], v148
	ds_read_b128 v[156:159], v148 offset:1024
	ds_read_b128 v[160:163], v148 offset:2048
	ds_read_b128 v[164:167], v148 offset:3072
	ds_read_b128 v[168:171], v149
	ds_read_b128 v[172:175], v149 offset:1024
	ds_read_b128 v[176:179], v149 offset:2048
	ds_read_b128 v[180:183], v149 offset:3072
	s_add_u32 s26, s24, 0xfffc0080
	s_addc_u32 s27, s25, -1
	s_cmp_eq_u32 s65, 12
	s_cselect_b32 s29, s17, s27
	s_cselect_b32 s28, s33, s26
	s_cselect_b32 s27, s15, s64
	s_cselect_b32 s26, s62, s63
	s_add_i32 m0, s23, 0xc000
	ds_read_b128 v[184:187], v150
	ds_read_b128 v[188:191], v150 offset:1024
	ds_read_b128 v[192:195], v150 offset:2048
	ds_read_b128 v[196:199], v150 offset:3072
	ds_read_b128 v[200:203], v150 offset:4096
	ds_read_b128 v[204:207], v150 offset:5120
	ds_read_b128 v[208:211], v150 offset:6144
	ds_read_b128 v[212:215], v150 offset:7168
	global_load_lds_dwordx4 v136, s[24:25]
	s_add_i32 m0, s23, 0xe000
	s_nop 0
	global_load_lds_dwordx4 v138, s[24:25]
	s_waitcnt vmcnt(8)
	s_waitcnt lgkmcnt(0)
	s_barrier
	s_setprio 1
	s_waitcnt lgkmcnt(0)
	v_mfma_f32_16x16x32_bf16 v[124:127], v[152:155], v[184:187], v[124:127]
	v_mfma_f32_16x16x32_bf16 v[116:119], v[160:163], v[184:187], v[116:119]
	v_mfma_f32_16x16x32_bf16 v[108:111], v[152:155], v[192:195], v[108:111]
	v_mfma_f32_16x16x32_bf16 v[100:103], v[160:163], v[192:195], v[100:103]
	v_mfma_f32_16x16x32_bf16 v[92:95], v[152:155], v[200:203], v[92:95]
	v_mfma_f32_16x16x32_bf16 v[84:87], v[160:163], v[200:203], v[84:87]
	v_mfma_f32_16x16x32_bf16 v[76:79], v[152:155], v[208:211], v[76:79]
	v_mfma_f32_16x16x32_bf16 v[68:71], v[160:163], v[208:211], v[68:71]
	v_mfma_f32_16x16x32_bf16 v[124:127], v[156:159], v[188:191], v[124:127]
	v_mfma_f32_16x16x32_bf16 v[116:119], v[164:167], v[188:191], v[116:119]
	v_mfma_f32_16x16x32_bf16 v[108:111], v[156:159], v[196:199], v[108:111]
	v_mfma_f32_16x16x32_bf16 v[100:103], v[164:167], v[196:199], v[100:103]
	v_mfma_f32_16x16x32_bf16 v[92:95], v[156:159], v[204:207], v[92:95]
	v_mfma_f32_16x16x32_bf16 v[84:87], v[164:167], v[204:207], v[84:87]
	v_mfma_f32_16x16x32_bf16 v[76:79], v[156:159], v[212:215], v[76:79]
	v_mfma_f32_16x16x32_bf16 v[68:71], v[164:167], v[212:215], v[68:71]
	v_mfma_f32_16x16x32_bf16 v[120:123], v[168:171], v[184:187], v[120:123]
	v_mfma_f32_16x16x32_bf16 v[112:115], v[176:179], v[184:187], v[112:115]
	v_mfma_f32_16x16x32_bf16 v[104:107], v[168:171], v[192:195], v[104:107]
	v_mfma_f32_16x16x32_bf16 v[96:99], v[176:179], v[192:195], v[96:99]
	v_mfma_f32_16x16x32_bf16 v[88:91], v[168:171], v[200:203], v[88:91]
	v_mfma_f32_16x16x32_bf16 v[80:83], v[176:179], v[200:203], v[80:83]
	v_mfma_f32_16x16x32_bf16 v[72:75], v[168:171], v[208:211], v[72:75]
	v_mfma_f32_16x16x32_bf16 v[64:67], v[176:179], v[208:211], v[64:67]
	v_mfma_f32_16x16x32_bf16 v[120:123], v[172:175], v[188:191], v[120:123]
	v_mfma_f32_16x16x32_bf16 v[112:115], v[180:183], v[188:191], v[112:115]
	v_mfma_f32_16x16x32_bf16 v[104:107], v[172:175], v[196:199], v[104:107]
	v_mfma_f32_16x16x32_bf16 v[96:99], v[180:183], v[196:199], v[96:99]
	v_mfma_f32_16x16x32_bf16 v[88:91], v[172:175], v[204:207], v[88:91]
	v_mfma_f32_16x16x32_bf16 v[80:83], v[180:183], v[204:207], v[80:83]
	v_mfma_f32_16x16x32_bf16 v[72:75], v[172:175], v[212:215], v[72:75]
	v_mfma_f32_16x16x32_bf16 v[64:67], v[180:183], v[212:215], v[64:67]
	s_setprio 0
	s_barrier
	s_add_i32 s66, s58, s50
	v_lshl_add_u64 v[216:217], s[26:27], 0, v[130:131]
	s_mov_b32 m0, s66
	ds_read_b128 v[184:187], v150 offset:16384
	ds_read_b128 v[188:191], v150 offset:17408
	ds_read_b128 v[192:195], v150 offset:18432
	ds_read_b128 v[196:199], v150 offset:19456
	ds_read_b128 v[200:203], v150 offset:20480
	ds_read_b128 v[204:207], v150 offset:21504
	ds_read_b128 v[208:211], v150 offset:22528
	ds_read_b128 v[212:215], v150 offset:23552
	global_load_lds_dwordx4 v[216:217], off
	s_add_i32 m0, s66, 0x2000
	s_add_u32 s66, s26, 0x40000
	v_lshl_add_u64 v[218:219], s[26:27], 0, v[134:135]
	s_addc_u32 s67, s27, 0
	s_add_i32 s72, s59, s50
	global_load_lds_dwordx4 v[218:219], off
	s_mov_b32 m0, s72
	v_lshl_add_u64 v[222:223], s[28:29], 0, v[132:133]
	global_load_lds_dwordx4 v130, s[66:67]
	s_add_i32 m0, s72, 0x2000
	s_nop 0
	global_load_lds_dwordx4 v134, s[66:67]
	v_lshl_add_u64 v[220:221], s[28:29], 0, v[128:129]
	s_mov_b32 m0, s23
	s_nop 0
	global_load_lds_dwordx4 v[220:221], off
	s_mov_b32 m0, s51
	s_nop 0
	global_load_lds_dwordx4 v[222:223], off
	s_waitcnt vmcnt(8)
	s_waitcnt lgkmcnt(0)
	s_barrier
	s_setprio 1
	s_waitcnt lgkmcnt(0)
	v_mfma_f32_16x16x32_bf16 v[60:63], v[152:155], v[184:187], v[60:63]
	v_mfma_f32_16x16x32_bf16 v[52:55], v[160:163], v[184:187], v[52:55]
	v_mfma_f32_16x16x32_bf16 v[44:47], v[152:155], v[192:195], v[44:47]
	v_mfma_f32_16x16x32_bf16 v[36:39], v[160:163], v[192:195], v[36:39]
	v_mfma_f32_16x16x32_bf16 v[28:31], v[152:155], v[200:203], v[28:31]
	v_mfma_f32_16x16x32_bf16 v[20:23], v[160:163], v[200:203], v[20:23]
	v_mfma_f32_16x16x32_bf16 v[12:15], v[152:155], v[208:211], v[12:15]
	v_mfma_f32_16x16x32_bf16 v[4:7], v[160:163], v[208:211], v[4:7]
	v_mfma_f32_16x16x32_bf16 v[60:63], v[156:159], v[188:191], v[60:63]
	v_mfma_f32_16x16x32_bf16 v[52:55], v[164:167], v[188:191], v[52:55]
	v_mfma_f32_16x16x32_bf16 v[44:47], v[156:159], v[196:199], v[44:47]
	v_mfma_f32_16x16x32_bf16 v[36:39], v[164:167], v[196:199], v[36:39]
	v_mfma_f32_16x16x32_bf16 v[28:31], v[156:159], v[204:207], v[28:31]
	v_mfma_f32_16x16x32_bf16 v[20:23], v[164:167], v[204:207], v[20:23]
	v_mfma_f32_16x16x32_bf16 v[12:15], v[156:159], v[212:215], v[12:15]
	v_mfma_f32_16x16x32_bf16 v[4:7], v[164:167], v[212:215], v[4:7]
	v_mfma_f32_16x16x32_bf16 v[56:59], v[168:171], v[184:187], v[56:59]
	v_mfma_f32_16x16x32_bf16 v[48:51], v[176:179], v[184:187], v[48:51]
	v_mfma_f32_16x16x32_bf16 v[40:43], v[168:171], v[192:195], v[40:43]
	v_mfma_f32_16x16x32_bf16 v[32:35], v[176:179], v[192:195], v[32:35]
	v_mfma_f32_16x16x32_bf16 v[24:27], v[168:171], v[200:203], v[24:27]
	v_mfma_f32_16x16x32_bf16 v[16:19], v[176:179], v[200:203], v[16:19]
	v_mfma_f32_16x16x32_bf16 v[8:11], v[168:171], v[208:211], v[8:11]
	v_mfma_f32_16x16x32_bf16 v[0:3], v[176:179], v[208:211], v[0:3]
	v_mfma_f32_16x16x32_bf16 v[56:59], v[172:175], v[188:191], v[56:59]
	v_mfma_f32_16x16x32_bf16 v[48:51], v[180:183], v[188:191], v[48:51]
	v_mfma_f32_16x16x32_bf16 v[40:43], v[172:175], v[196:199], v[40:43]
	v_mfma_f32_16x16x32_bf16 v[32:35], v[180:183], v[196:199], v[32:35]
	v_mfma_f32_16x16x32_bf16 v[24:27], v[172:175], v[204:207], v[24:27]
	v_mfma_f32_16x16x32_bf16 v[16:19], v[180:183], v[204:207], v[16:19]
	v_mfma_f32_16x16x32_bf16 v[8:11], v[172:175], v[212:215], v[8:11]
	v_mfma_f32_16x16x32_bf16 v[0:3], v[180:183], v[212:215], v[0:3]
	s_setprio 0
	s_barrier
; #define PG8_STAGE(bufoff, gbase, voff) do { _Pragma("unroll") for (int _i = 0; _i < 2; ++_i) \
;         __builtin_amdgcn_global_load_lds((const unsigned*)((const char*)(gbase) + (voff)[_i]), (PG8_LAS unsigned*)(lds + (bufoff) + ldsw + _i * 8192), 16, 0, 0); } while (0)
; #define PG8_LDA(dst, b, h) do { _Pragma("unroll") for (int m = 0; m < 4; ++m) _Pragma("unroll") for (int k = 0; k < 2; ++k) dst[m][k] = *(const PG8_LAS bf16x8*)(lds + PG8_SA(b, h) + aoff + m * 2048 + k * 1024); } while (0)
; #define PG8_LDB(dst, b, h) do { _Pragma("unroll") for (int n = 0; n < 2; ++n) _Pragma("unroll") for (int k = 0; k < 2; ++k) dst[n][k] = *(const PG8_LAS bf16x8*)(lds + PG8_SB(b, h) + boff + n * 2048 + k * 1024); } while (0)
; #define PG8_MMA(ai, bj, At, Bt) do { __builtin_amdgcn_s_setprio(1); _Pragma("unroll") for (int m = 0; m < 4; ++m) _Pragma("unroll") for (int n = 0; n < 2; ++n) _Pragma("unroll") for (int k = 0; k < 2; ++k) \
;         acc[ai][bj][m][n] = __builtin_amdgcn_mfma_f32_16x16x32_bf16(Bt[n][k], At[m][k], acc[ai][bj][m][n], 0, 0, 0); __builtin_amdgcn_s_setprio(0); } while (0)
; #define PG8_WAIT_V(n) asm volatile("s_waitcnt vmcnt(" #n ")" ::: "memory")
; #define PG8_WAIT_L(n) asm volatile("s_waitcnt lgkmcnt(" #n ")" ::: "memory")
; #define PG8_BAR __builtin_amdgcn_s_barrier()
; #define PG8_SCHED __builtin_amdgcn_sched_barrier(0)
; template <class Epi, class Sched, bool ALIGN_EPI = false, bool SP2 = false>
; __device__ __forceinline__ void gemm_phase(PG8_LAS unsigned char* lds, const Gemm g, const Sched& S, const Epi& E, const int tid) {
;     ...
;             PG8_LDB(B0, 1, 0); PG8_LDB(B1, 1, 1); PG8_SCHED; PG8_LDA(At, 1, 0); PG8_STAGE(PG8_SA(0, 1), a2 + hstep, voffA);
;             PG8_WAIT_V(8); PG8_WAIT_L(0); PG8_BAR; PG8_MMA(0, 0, At, B0); PG8_MMA(0, 1, At, B1); PG8_BAR; PG8_SCHED;
;             PG8_LDA(At, 1, 1); PG8_STAGE(PG8_SB(1, 0), b3, voffB); PG8_STAGE(PG8_SB(1, 1), b3 + hstep, voffB); PG8_STAGE(PG8_SA(1, 0), a3, voffA);
;             PG8_WAIT_V(8); PG8_WAIT_L(0); PG8_BAR; PG8_MMA(1, 0, At, B0); PG8_MMA(1, 1, At, B1); PG8_BAR; PG8_SCHED;
	s_add_i32 s66, 0, 0x18000
	v_add_u32_e32 v151, s66, v146
	s_add_i32 s67, 0, 0x1c000
	ds_read_b128 v[152:155], v151
	ds_read_b128 v[156:159], v151 offset:1024
	ds_read_b128 v[160:163], v151 offset:2048
	ds_read_b128 v[164:167], v151 offset:3072
	v_add_u32_e32 v151, s67, v146
	ds_read_b128 v[168:171], v151
	ds_read_b128 v[172:175], v151 offset:1024
	ds_read_b128 v[176:179], v151 offset:2048
	ds_read_b128 v[180:183], v151 offset:3072
	s_add_u32 s28, s28, 0x40000
	s_addc_u32 s29, s29, 0
	s_mov_b32 m0, s52
	ds_read_b128 v[184:187], v150 offset:32768
	ds_read_b128 v[188:191], v150 offset:33792
	ds_read_b128 v[192:195], v150 offset:34816
	ds_read_b128 v[196:199], v150 offset:35840
	ds_read_b128 v[200:203], v150 offset:36864
	ds_read_b128 v[204:207], v150 offset:37888
	ds_read_b128 v[208:211], v150 offset:38912
	ds_read_b128 v[212:215], v150 offset:39936
	global_load_lds_dwordx4 v128, s[28:29]
	v_lshl_add_u64 v[224:225], s[28:29], 0, v[132:133]
	s_mov_b32 m0, s53
	s_nop 0
	global_load_lds_dwordx4 v[224:225], off
	s_waitcnt vmcnt(8)
	s_waitcnt lgkmcnt(0)
	s_barrier
	s_setprio 1
	s_waitcnt lgkmcnt(0)
	v_mfma_f32_16x16x32_bf16 v[124:127], v[152:155], v[184:187], v[124:127]
	v_mfma_f32_16x16x32_bf16 v[116:119], v[160:163], v[184:187], v[116:119]
	v_mfma_f32_16x16x32_bf16 v[108:111], v[152:155], v[192:195], v[108:111]
	v_mfma_f32_16x16x32_bf16 v[100:103], v[160:163], v[192:195], v[100:103]
	v_mfma_f32_16x16x32_bf16 v[92:95], v[152:155], v[200:203], v[92:95]
	v_mfma_f32_16x16x32_bf16 v[84:87], v[160:163], v[200:203], v[84:87]
	v_mfma_f32_16x16x32_bf16 v[76:79], v[152:155], v[208:211], v[76:79]
	v_mfma_f32_16x16x32_bf16 v[68:71], v[160:163], v[208:211], v[68:71]
	v_mfma_f32_16x16x32_bf16 v[124:127], v[156:159], v[188:191], v[124:127]
	v_mfma_f32_16x16x32_bf16 v[116:119], v[164:167], v[188:191], v[116:119]
	v_mfma_f32_16x16x32_bf16 v[108:111], v[156:159], v[196:199], v[108:111]
	v_mfma_f32_16x16x32_bf16 v[100:103], v[164:167], v[196:199], v[100:103]
	v_mfma_f32_16x16x32_bf16 v[92:95], v[156:159], v[204:207], v[92:95]
	v_mfma_f32_16x16x32_bf16 v[84:87], v[164:167], v[204:207], v[84:87]
	v_mfma_f32_16x16x32_bf16 v[76:79], v[156:159], v[212:215], v[76:79]
	v_mfma_f32_16x16x32_bf16 v[68:71], v[164:167], v[212:215], v[68:71]
	v_mfma_f32_16x16x32_bf16 v[120:123], v[168:171], v[184:187], v[120:123]
	v_mfma_f32_16x16x32_bf16 v[112:115], v[176:179], v[184:187], v[112:115]
	v_mfma_f32_16x16x32_bf16 v[104:107], v[168:171], v[192:195], v[104:107]
	v_mfma_f32_16x16x32_bf16 v[96:99], v[176:179], v[192:195], v[96:99]
	v_mfma_f32_16x16x32_bf16 v[88:91], v[168:171], v[200:203], v[88:91]
	v_mfma_f32_16x16x32_bf16 v[80:83], v[176:179], v[200:203], v[80:83]
	v_mfma_f32_16x16x32_bf16 v[72:75], v[168:171], v[208:211], v[72:75]
	v_mfma_f32_16x16x32_bf16 v[64:67], v[176:179], v[208:211], v[64:67]
	v_mfma_f32_16x16x32_bf16 v[120:123], v[172:175], v[188:191], v[120:123]
	v_mfma_f32_16x16x32_bf16 v[112:115], v[180:183], v[188:191], v[112:115]
	v_mfma_f32_16x16x32_bf16 v[104:107], v[172:175], v[196:199], v[104:107]
	v_mfma_f32_16x16x32_bf16 v[96:99], v[180:183], v[196:199], v[96:99]
	v_mfma_f32_16x16x32_bf16 v[88:91], v[172:175], v[204:207], v[88:91]
	v_mfma_f32_16x16x32_bf16 v[80:83], v[180:183], v[204:207], v[80:83]
	v_mfma_f32_16x16x32_bf16 v[72:75], v[172:175], v[212:215], v[72:75]
	v_mfma_f32_16x16x32_bf16 v[64:67], v[180:183], v[212:215], v[64:67]
	s_setprio 0
	s_barrier
	s_add_i32 s28, s66, s50
	v_lshl_add_u64 v[216:217], v[216:217], 0, s[10:11]
	s_mov_b32 m0, s28
	ds_read_b128 v[184:187], v150 offset:49152
	ds_read_b128 v[188:191], v150 offset:50176
	ds_read_b128 v[192:195], v150 offset:51200
	ds_read_b128 v[196:199], v150 offset:52224
	ds_read_b128 v[200:203], v150 offset:53248
	ds_read_b128 v[204:207], v150 offset:54272
	ds_read_b128 v[208:211], v150 offset:55296
	ds_read_b128 v[212:215], v150 offset:56320
	global_load_lds_dwordx4 v[216:217], off
	s_add_i32 m0, s28, 0x2000
	s_add_u32 s26, s26, 0x40080
	v_lshl_add_u64 v[216:217], v[218:219], 0, s[10:11]
	s_addc_u32 s27, s27, 0
	s_add_i32 s28, s67, s50
	global_load_lds_dwordx4 v[216:217], off
	s_mov_b32 m0, s28
	s_nop 0
	global_load_lds_dwordx4 v130, s[26:27]
	s_add_i32 m0, s28, 0x2000
	s_nop 0
	global_load_lds_dwordx4 v134, s[26:27]
	v_lshl_add_u64 v[216:217], v[220:221], 0, s[10:11]
	s_mov_b32 m0, s55
	s_nop 0
	global_load_lds_dwordx4 v[216:217], off
	v_lshl_add_u64 v[216:217], v[222:223], 0, s[10:11]
	s_mov_b32 m0, s56
	s_nop 0
	global_load_lds_dwordx4 v[216:217], off
	s_waitcnt vmcnt(8)
	s_waitcnt lgkmcnt(0)
	s_barrier
	s_setprio 1
	s_waitcnt lgkmcnt(0)
	v_mfma_f32_16x16x32_bf16 v[60:63], v[152:155], v[184:187], v[60:63]
	v_mfma_f32_16x16x32_bf16 v[52:55], v[160:163], v[184:187], v[52:55]
	v_mfma_f32_16x16x32_bf16 v[44:47], v[152:155], v[192:195], v[44:47]
	v_mfma_f32_16x16x32_bf16 v[36:39], v[160:163], v[192:195], v[36:39]
	v_mfma_f32_16x16x32_bf16 v[28:31], v[152:155], v[200:203], v[28:31]
	v_mfma_f32_16x16x32_bf16 v[20:23], v[160:163], v[200:203], v[20:23]
	v_mfma_f32_16x16x32_bf16 v[12:15], v[152:155], v[208:211], v[12:15]
	v_mfma_f32_16x16x32_bf16 v[4:7], v[160:163], v[208:211], v[4:7]
	v_mfma_f32_16x16x32_bf16 v[60:63], v[156:159], v[188:191], v[60:63]
	v_mfma_f32_16x16x32_bf16 v[52:55], v[164:167], v[188:191], v[52:55]
	v_mfma_f32_16x16x32_bf16 v[44:47], v[156:159], v[196:199], v[44:47]
	v_mfma_f32_16x16x32_bf16 v[36:39], v[164:167], v[196:199], v[36:39]
	v_mfma_f32_16x16x32_bf16 v[28:31], v[156:159], v[204:207], v[28:31]
	v_mfma_f32_16x16x32_bf16 v[20:23], v[164:167], v[204:207], v[20:23]
	v_mfma_f32_16x16x32_bf16 v[12:15], v[156:159], v[212:215], v[12:15]
	v_mfma_f32_16x16x32_bf16 v[4:7], v[164:167], v[212:215], v[4:7]
	v_mfma_f32_16x16x32_bf16 v[56:59], v[168:171], v[184:187], v[56:59]
	v_mfma_f32_16x16x32_bf16 v[48:51], v[176:179], v[184:187], v[48:51]
	v_mfma_f32_16x16x32_bf16 v[40:43], v[168:171], v[192:195], v[40:43]
	v_mfma_f32_16x16x32_bf16 v[32:35], v[176:179], v[192:195], v[32:35]
	v_mfma_f32_16x16x32_bf16 v[24:27], v[168:171], v[200:203], v[24:27]
	v_mfma_f32_16x16x32_bf16 v[16:19], v[176:179], v[200:203], v[16:19]
	v_mfma_f32_16x16x32_bf16 v[8:11], v[168:171], v[208:211], v[8:11]
	v_mfma_f32_16x16x32_bf16 v[0:3], v[176:179], v[208:211], v[0:3]
	v_mfma_f32_16x16x32_bf16 v[56:59], v[172:175], v[188:191], v[56:59]
	v_mfma_f32_16x16x32_bf16 v[48:51], v[180:183], v[188:191], v[48:51]
	v_mfma_f32_16x16x32_bf16 v[40:43], v[172:175], v[196:199], v[40:43]
	v_mfma_f32_16x16x32_bf16 v[32:35], v[180:183], v[196:199], v[32:35]
	v_mfma_f32_16x16x32_bf16 v[24:27], v[172:175], v[204:207], v[24:27]
	v_mfma_f32_16x16x32_bf16 v[16:19], v[180:183], v[204:207], v[16:19]
	v_mfma_f32_16x16x32_bf16 v[8:11], v[172:175], v[212:215], v[8:11]
	v_mfma_f32_16x16x32_bf16 v[0:3], v[180:183], v[212:215], v[0:3]
	s_setprio 0
	s_barrier
	s_add_i32 s65, s65, 2
	s_add_u32 s24, s24, 0x100
	s_addc_u32 s25, s25, 0
	s_add_u32 s63, s63, 0x100
	s_addc_u32 s64, s64, 0
	s_cmp_gt_u32 s65, 13
	s_cbranch_scc0 .LBB0_813
	s_and_b64 vcc, exec, s[12:13]
	s_cbranch_vccz .LBB0_816
	s_barrier

; #define PG8_STAGE(bufoff, gbase, voff) do { _Pragma("unroll") for (int _i = 0; _i < 2; ++_i) \
;         __builtin_amdgcn_global_load_lds((const unsigned*)((const char*)(gbase) + (voff)[_i]), (PG8_LAS unsigned*)(lds + (bufoff) + ldsw + _i * 8192), 16, 0, 0); } while (0)
; #define PG8_LDA(dst, b, h) do { _Pragma("unroll") for (int m = 0; m < 4; ++m) _Pragma("unroll") for (int k = 0; k < 2; ++k) dst[m][k] = *(const PG8_LAS bf16x8*)(lds + PG8_SA(b, h) + aoff + m * 2048 + k * 1024); } while (0)
; #define PG8_LDB(dst, b, h) do { _Pragma("unroll") for (int n = 0; n < 2; ++n) _Pragma("unroll") for (int k = 0; k < 2; ++k) dst[n][k] = *(const PG8_LAS bf16x8*)(lds + PG8_SB(b, h) + boff + n * 2048 + k * 1024); } while (0)
; #define PG8_MMA(ai, bj, At, Bt) do { __builtin_amdgcn_s_setprio(1); _Pragma("unroll") for (int m = 0; m < 4; ++m) _Pragma("unroll") for (int n = 0; n < 2; ++n) _Pragma("unroll") for (int k = 0; k < 2; ++k) \
;         acc[ai][bj][m][n] = __builtin_amdgcn_mfma_f32_16x16x32_bf16(Bt[n][k], At[m][k], acc[ai][bj][m][n], 0, 0, 0); __builtin_amdgcn_s_setprio(0); } while (0)
; #define PG8_WAIT_V(n) asm volatile("s_waitcnt vmcnt(" #n ")" ::: "memory")
; #define PG8_WAIT_L(n) asm volatile("s_waitcnt lgkmcnt(" #n ")" ::: "memory")
; #define PG8_BAR __builtin_amdgcn_s_barrier()
; #define PG8_SCHED __builtin_amdgcn_sched_barrier(0)
; template <class Epi, class Sched, bool ALIGN_EPI = false, bool SP2 = false>
; __device__ __forceinline__ void gemm_phase(PG8_LAS unsigned char* lds, const Gemm g, const Sched& S, const Epi& E, const int tid) {
;     ...
;             PG8_LDB(B0, 0, 0); PG8_LDB(B1, 0, 1); PG8_SCHED; PG8_LDA(At, 0, 0); PG8_STAGE(PG8_SA(1, 1), a1 + hstep, voffA);
;             PG8_WAIT_V(8); PG8_WAIT_L(0); PG8_BAR; PG8_MMA(0, 0, At, B0); PG8_MMA(0, 1, At, B1); PG8_BAR; PG8_SCHED;
;             PG8_LDA(At, 0, 1); PG8_STAGE(PG8_SB(0, 0), b2, voffB); PG8_STAGE(PG8_SB(0, 1), b2 + hstep, voffB); PG8_STAGE(PG8_SA(0, 0), a2, voffA);
;             PG8_WAIT_V(8); PG8_WAIT_L(0); PG8_BAR; PG8_MMA(1, 0, At, B0); PG8_MMA(1, 1, At, B1); PG8_BAR; PG8_SCHED;
.LBB0_989:
	ds_read_b128 v[120:123], v180
	ds_read_b128 v[124:127], v180 offset:1024
	ds_read_b128 v[136:139], v180 offset:2048
	ds_read_b128 v[140:143], v180 offset:3072
	ds_read_b128 v[184:187], v181
	ds_read_b128 v[188:191], v181 offset:1024
	ds_read_b128 v[192:195], v181 offset:2048
	ds_read_b128 v[196:199], v181 offset:3072
	s_add_u32 s20, s18, 0x100
	s_addc_u32 s21, s19, 0
	s_cmp_eq_u32 s55, 40
	s_cselect_b32 s25, s3, s21
	s_cselect_b32 s24, s2, s20
	s_cselect_b32 s23, s17, s54
	s_cselect_b32 s22, s16, s33
	s_add_i32 m0, s36, 0xc000
	ds_read_b128 v[200:203], v182
	ds_read_b128 v[204:207], v182 offset:1024
	ds_read_b128 v[208:211], v182 offset:2048
	ds_read_b128 v[212:215], v182 offset:3072
	ds_read_b128 v[216:219], v182 offset:4096
	ds_read_b128 v[220:223], v182 offset:5120
	ds_read_b128 v[224:227], v182 offset:6144
	ds_read_b128 v[228:231], v182 offset:7168
	global_load_lds_dwordx4 v168, s[18:19]
	s_add_i32 m0, s36, 0xe000
	s_nop 0
	global_load_lds_dwordx4 v170, s[18:19]
	s_waitcnt vmcnt(8)
	s_waitcnt lgkmcnt(0)
	s_barrier
	s_setprio 1
	s_waitcnt lgkmcnt(0)
	v_mfma_f32_16x16x32_bf16 v[132:135], v[120:123], v[200:203], v[132:135]
	v_mfma_f32_16x16x32_bf16 v[128:131], v[136:139], v[200:203], v[128:131]
	v_mfma_f32_16x16x32_bf16 v[116:119], v[120:123], v[208:211], v[116:119]
	v_mfma_f32_16x16x32_bf16 v[104:107], v[136:139], v[208:211], v[104:107]
	v_mfma_f32_16x16x32_bf16 v[100:103], v[120:123], v[216:219], v[100:103]
	v_mfma_f32_16x16x32_bf16 v[88:91], v[136:139], v[216:219], v[88:91]
	v_mfma_f32_16x16x32_bf16 v[84:87], v[120:123], v[224:227], v[84:87]
	v_mfma_f32_16x16x32_bf16 v[72:75], v[136:139], v[224:227], v[72:75]
	v_mfma_f32_16x16x32_bf16 v[132:135], v[124:127], v[204:207], v[132:135]
	v_mfma_f32_16x16x32_bf16 v[128:131], v[140:143], v[204:207], v[128:131]
	v_mfma_f32_16x16x32_bf16 v[116:119], v[124:127], v[212:215], v[116:119]
	v_mfma_f32_16x16x32_bf16 v[104:107], v[140:143], v[212:215], v[104:107]
	v_mfma_f32_16x16x32_bf16 v[100:103], v[124:127], v[220:223], v[100:103]
	v_mfma_f32_16x16x32_bf16 v[88:91], v[140:143], v[220:223], v[88:91]
	v_mfma_f32_16x16x32_bf16 v[84:87], v[124:127], v[228:231], v[84:87]
	v_mfma_f32_16x16x32_bf16 v[72:75], v[140:143], v[228:231], v[72:75]
	v_mfma_f32_16x16x32_bf16 v[112:115], v[184:187], v[200:203], v[112:115]
	v_mfma_f32_16x16x32_bf16 v[108:111], v[192:195], v[200:203], v[108:111]
	v_mfma_f32_16x16x32_bf16 v[96:99], v[184:187], v[208:211], v[96:99]
	v_mfma_f32_16x16x32_bf16 v[92:95], v[192:195], v[208:211], v[92:95]
	v_mfma_f32_16x16x32_bf16 v[80:83], v[184:187], v[216:219], v[80:83]
	v_mfma_f32_16x16x32_bf16 v[76:79], v[192:195], v[216:219], v[76:79]
	v_mfma_f32_16x16x32_bf16 v[68:71], v[184:187], v[224:227], v[68:71]
	v_mfma_f32_16x16x32_bf16 v[64:67], v[192:195], v[224:227], v[64:67]
	v_mfma_f32_16x16x32_bf16 v[112:115], v[188:191], v[204:207], v[112:115]
	v_mfma_f32_16x16x32_bf16 v[108:111], v[196:199], v[204:207], v[108:111]
	v_mfma_f32_16x16x32_bf16 v[96:99], v[188:191], v[212:215], v[96:99]
	v_mfma_f32_16x16x32_bf16 v[92:95], v[196:199], v[212:215], v[92:95]
	v_mfma_f32_16x16x32_bf16 v[80:83], v[188:191], v[220:223], v[80:83]
	v_mfma_f32_16x16x32_bf16 v[76:79], v[196:199], v[220:223], v[76:79]
	v_mfma_f32_16x16x32_bf16 v[68:71], v[188:191], v[228:231], v[68:71]
	v_mfma_f32_16x16x32_bf16 v[64:67], v[196:199], v[228:231], v[64:67]
	s_setprio 0
	s_barrier
	s_add_i32 s18, s48, s35
	v_lshl_add_u64 v[176:177], s[22:23], 0, v[146:147]
	s_mov_b32 m0, s18
	ds_read_b128 v[200:203], v182 offset:16384
	ds_read_b128 v[204:207], v182 offset:17408
	ds_read_b128 v[208:211], v182 offset:18432
	ds_read_b128 v[212:215], v182 offset:19456
	ds_read_b128 v[216:219], v182 offset:20480
	ds_read_b128 v[220:223], v182 offset:21504
	ds_read_b128 v[224:227], v182 offset:22528
	ds_read_b128 v[228:231], v182 offset:23552
	global_load_lds_dwordx4 v[176:177], off
	s_add_i32 m0, s18, 0x2000
	s_add_u32 s18, s22, 0xb0000
	v_lshl_add_u64 v[232:233], s[22:23], 0, v[150:151]
	s_addc_u32 s19, s23, 0
	s_add_i32 s56, s49, s35
	global_load_lds_dwordx4 v[232:233], off
	s_mov_b32 m0, s56
	v_lshl_add_u64 v[236:237], s[24:25], 0, v[148:149]
	global_load_lds_dwordx4 v146, s[18:19]
	s_add_i32 m0, s56, 0x2000
	s_nop 0
	global_load_lds_dwordx4 v150, s[18:19]
	v_lshl_add_u64 v[234:235], s[24:25], 0, v[144:145]
	s_mov_b32 m0, s36
	s_nop 0
	global_load_lds_dwordx4 v[234:235], off
	s_mov_b32 m0, s37
	s_nop 0
	global_load_lds_dwordx4 v[236:237], off
	s_waitcnt vmcnt(8)
	s_waitcnt lgkmcnt(0)
	s_barrier
	s_setprio 1
	s_waitcnt lgkmcnt(0)
	v_mfma_f32_16x16x32_bf16 v[60:63], v[120:123], v[200:203], v[60:63]
	v_mfma_f32_16x16x32_bf16 v[56:59], v[136:139], v[200:203], v[56:59]
	v_mfma_f32_16x16x32_bf16 v[52:55], v[120:123], v[208:211], v[52:55]
	v_mfma_f32_16x16x32_bf16 v[40:43], v[136:139], v[208:211], v[40:43]
	v_mfma_f32_16x16x32_bf16 v[36:39], v[120:123], v[216:219], v[36:39]
	v_mfma_f32_16x16x32_bf16 v[24:27], v[136:139], v[216:219], v[24:27]
	v_mfma_f32_16x16x32_bf16 v[20:23], v[120:123], v[224:227], v[20:23]
	v_mfma_f32_16x16x32_bf16 v[8:11], v[136:139], v[224:227], v[8:11]
	v_mfma_f32_16x16x32_bf16 v[60:63], v[124:127], v[204:207], v[60:63]
	v_mfma_f32_16x16x32_bf16 v[56:59], v[140:143], v[204:207], v[56:59]
	v_mfma_f32_16x16x32_bf16 v[52:55], v[124:127], v[212:215], v[52:55]
	v_mfma_f32_16x16x32_bf16 v[40:43], v[140:143], v[212:215], v[40:43]
	v_mfma_f32_16x16x32_bf16 v[36:39], v[124:127], v[220:223], v[36:39]
	v_mfma_f32_16x16x32_bf16 v[24:27], v[140:143], v[220:223], v[24:27]
	v_mfma_f32_16x16x32_bf16 v[20:23], v[124:127], v[228:231], v[20:23]
	v_mfma_f32_16x16x32_bf16 v[8:11], v[140:143], v[228:231], v[8:11]
	v_mfma_f32_16x16x32_bf16 v[48:51], v[184:187], v[200:203], v[48:51]
	v_mfma_f32_16x16x32_bf16 v[44:47], v[192:195], v[200:203], v[44:47]
	v_mfma_f32_16x16x32_bf16 v[32:35], v[184:187], v[208:211], v[32:35]
	v_mfma_f32_16x16x32_bf16 v[28:31], v[192:195], v[208:211], v[28:31]
	v_mfma_f32_16x16x32_bf16 v[16:19], v[184:187], v[216:219], v[16:19]
	v_mfma_f32_16x16x32_bf16 v[12:15], v[192:195], v[216:219], v[12:15]
	v_mfma_f32_16x16x32_bf16 v[4:7], v[184:187], v[224:227], v[4:7]
	v_mfma_f32_16x16x32_bf16 v[0:3], v[192:195], v[224:227], v[0:3]
	v_mfma_f32_16x16x32_bf16 v[48:51], v[188:191], v[204:207], v[48:51]
	v_mfma_f32_16x16x32_bf16 v[44:47], v[196:199], v[204:207], v[44:47]
	v_mfma_f32_16x16x32_bf16 v[32:35], v[188:191], v[212:215], v[32:35]
	v_mfma_f32_16x16x32_bf16 v[28:31], v[196:199], v[212:215], v[28:31]
	v_mfma_f32_16x16x32_bf16 v[16:19], v[188:191], v[220:223], v[16:19]
	v_mfma_f32_16x16x32_bf16 v[12:15], v[196:199], v[220:223], v[12:15]
	v_mfma_f32_16x16x32_bf16 v[4:7], v[188:191], v[228:231], v[4:7]
	v_mfma_f32_16x16x32_bf16 v[0:3], v[196:199], v[228:231], v[0:3]
	s_setprio 0
	s_barrier
; #define PG8_STAGE(bufoff, gbase, voff) do { _Pragma("unroll") for (int _i = 0; _i < 2; ++_i) \
;         __builtin_amdgcn_global_load_lds((const unsigned*)((const char*)(gbase) + (voff)[_i]), (PG8_LAS unsigned*)(lds + (bufoff) + ldsw + _i * 8192), 16, 0, 0); } while (0)
; #define PG8_LDA(dst, b, h) do { _Pragma("unroll") for (int m = 0; m < 4; ++m) _Pragma("unroll") for (int k = 0; k < 2; ++k) dst[m][k] = *(const PG8_LAS bf16x8*)(lds + PG8_SA(b, h) + aoff + m * 2048 + k * 1024); } while (0)
; #define PG8_LDB(dst, b, h) do { _Pragma("unroll") for (int n = 0; n < 2; ++n) _Pragma("unroll") for (int k = 0; k < 2; ++k) dst[n][k] = *(const PG8_LAS bf16x8*)(lds + PG8_SB(b, h) + boff + n * 2048 + k * 1024); } while (0)
; #define PG8_MMA(ai, bj, At, Bt) do { __builtin_amdgcn_s_setprio(1); _Pragma("unroll") for (int m = 0; m < 4; ++m) _Pragma("unroll") for (int n = 0; n < 2; ++n) _Pragma("unroll") for (int k = 0; k < 2; ++k) \
;         acc[ai][bj][m][n] = __builtin_amdgcn_mfma_f32_16x16x32_bf16(Bt[n][k], At[m][k], acc[ai][bj][m][n], 0, 0, 0); __builtin_amdgcn_s_setprio(0); } while (0)
; #define PG8_WAIT_V(n) asm volatile("s_waitcnt vmcnt(" #n ")" ::: "memory")
; #define PG8_WAIT_L(n) asm volatile("s_waitcnt lgkmcnt(" #n ")" ::: "memory")
; #define PG8_BAR __builtin_amdgcn_s_barrier()
; #define PG8_SCHED __builtin_amdgcn_sched_barrier(0)
; template <class Epi, class Sched, bool ALIGN_EPI = false, bool SP2 = false>
; __device__ __forceinline__ void gemm_phase(PG8_LAS unsigned char* lds, const Gemm g, const Sched& S, const Epi& E, const int tid) {
;     ...
;             PG8_LDB(B0, 1, 0); PG8_LDB(B1, 1, 1); PG8_SCHED; PG8_LDA(At, 1, 0); PG8_STAGE(PG8_SA(0, 1), a2 + hstep, voffA);
;             PG8_WAIT_V(8); PG8_WAIT_L(0); PG8_BAR; PG8_MMA(0, 0, At, B0); PG8_MMA(0, 1, At, B1); PG8_BAR; PG8_SCHED;
;             PG8_LDA(At, 1, 1); PG8_STAGE(PG8_SB(1, 0), b3, voffB); PG8_STAGE(PG8_SB(1, 1), b3 + hstep, voffB); PG8_STAGE(PG8_SA(1, 0), a3, voffA);
;             PG8_WAIT_V(8); PG8_WAIT_L(0); PG8_BAR; PG8_MMA(1, 0, At, B0); PG8_MMA(1, 1, At, B1); PG8_BAR; PG8_SCHED;
	s_add_i32 s56, 0, 0x18000
	s_add_i32 s57, 0, 0x1c000
	v_add_u32_e32 v140, s56, v178
	v_add_u32_e32 v183, s57, v178
	ds_read_b128 v[120:123], v140
	ds_read_b128 v[124:127], v140 offset:1024
	ds_read_b128 v[136:139], v140 offset:2048
	ds_read_b128 v[140:143], v140 offset:3072
	ds_read_b128 v[184:187], v183
	ds_read_b128 v[188:191], v183 offset:1024
	ds_read_b128 v[192:195], v183 offset:2048
	ds_read_b128 v[196:199], v183 offset:3072
	s_add_u32 s18, s24, 0xb0000
	s_addc_u32 s19, s25, 0
	s_mov_b32 m0, s38
	ds_read_b128 v[200:203], v182 offset:32768
	ds_read_b128 v[204:207], v182 offset:33792
	ds_read_b128 v[208:211], v182 offset:34816
	ds_read_b128 v[212:215], v182 offset:35840
	ds_read_b128 v[216:219], v182 offset:36864
	ds_read_b128 v[220:223], v182 offset:37888
	ds_read_b128 v[224:227], v182 offset:38912
	ds_read_b128 v[228:231], v182 offset:39936
	global_load_lds_dwordx4 v144, s[18:19]
	v_lshl_add_u64 v[238:239], s[18:19], 0, v[148:149]
	s_mov_b32 m0, s39
	s_nop 0
	global_load_lds_dwordx4 v[238:239], off
	s_waitcnt vmcnt(8)
	s_waitcnt lgkmcnt(0)
	s_barrier
	s_setprio 1
	s_waitcnt lgkmcnt(0)
	v_mfma_f32_16x16x32_bf16 v[132:135], v[120:123], v[200:203], v[132:135]
	v_mfma_f32_16x16x32_bf16 v[128:131], v[136:139], v[200:203], v[128:131]
	v_mfma_f32_16x16x32_bf16 v[116:119], v[120:123], v[208:211], v[116:119]
	v_mfma_f32_16x16x32_bf16 v[104:107], v[136:139], v[208:211], v[104:107]
	v_mfma_f32_16x16x32_bf16 v[100:103], v[120:123], v[216:219], v[100:103]
	v_mfma_f32_16x16x32_bf16 v[88:91], v[136:139], v[216:219], v[88:91]
	v_mfma_f32_16x16x32_bf16 v[84:87], v[120:123], v[224:227], v[84:87]
	v_mfma_f32_16x16x32_bf16 v[72:75], v[136:139], v[224:227], v[72:75]
	v_mfma_f32_16x16x32_bf16 v[132:135], v[124:127], v[204:207], v[132:135]
	v_mfma_f32_16x16x32_bf16 v[128:131], v[140:143], v[204:207], v[128:131]
	v_mfma_f32_16x16x32_bf16 v[116:119], v[124:127], v[212:215], v[116:119]
	v_mfma_f32_16x16x32_bf16 v[104:107], v[140:143], v[212:215], v[104:107]
	v_mfma_f32_16x16x32_bf16 v[100:103], v[124:127], v[220:223], v[100:103]
	v_mfma_f32_16x16x32_bf16 v[88:91], v[140:143], v[220:223], v[88:91]
	v_mfma_f32_16x16x32_bf16 v[84:87], v[124:127], v[228:231], v[84:87]
	v_mfma_f32_16x16x32_bf16 v[72:75], v[140:143], v[228:231], v[72:75]
	v_mfma_f32_16x16x32_bf16 v[112:115], v[184:187], v[200:203], v[112:115]
	v_mfma_f32_16x16x32_bf16 v[108:111], v[192:195], v[200:203], v[108:111]
	v_mfma_f32_16x16x32_bf16 v[96:99], v[184:187], v[208:211], v[96:99]
	v_mfma_f32_16x16x32_bf16 v[92:95], v[192:195], v[208:211], v[92:95]
	v_mfma_f32_16x16x32_bf16 v[80:83], v[184:187], v[216:219], v[80:83]
	v_mfma_f32_16x16x32_bf16 v[76:79], v[192:195], v[216:219], v[76:79]
	v_mfma_f32_16x16x32_bf16 v[68:71], v[184:187], v[224:227], v[68:71]
	v_mfma_f32_16x16x32_bf16 v[64:67], v[192:195], v[224:227], v[64:67]
	v_mfma_f32_16x16x32_bf16 v[112:115], v[188:191], v[204:207], v[112:115]
	v_mfma_f32_16x16x32_bf16 v[108:111], v[196:199], v[204:207], v[108:111]
	v_mfma_f32_16x16x32_bf16 v[96:99], v[188:191], v[212:215], v[96:99]
	v_mfma_f32_16x16x32_bf16 v[92:95], v[196:199], v[212:215], v[92:95]
	v_mfma_f32_16x16x32_bf16 v[80:83], v[188:191], v[220:223], v[80:83]
	v_mfma_f32_16x16x32_bf16 v[76:79], v[196:199], v[220:223], v[76:79]
	v_mfma_f32_16x16x32_bf16 v[68:71], v[188:191], v[228:231], v[68:71]
	v_mfma_f32_16x16x32_bf16 v[64:67], v[196:199], v[228:231], v[64:67]
	s_setprio 0
	s_barrier
	s_add_i32 s18, s56, s35
	v_lshl_add_u64 v[176:177], v[176:177], 0, s[12:13]
	s_mov_b32 m0, s18
	ds_read_b128 v[200:203], v182 offset:49152
	ds_read_b128 v[204:207], v182 offset:50176
	ds_read_b128 v[208:211], v182 offset:51200
	ds_read_b128 v[212:215], v182 offset:52224
	ds_read_b128 v[216:219], v182 offset:53248
	ds_read_b128 v[220:223], v182 offset:54272
	ds_read_b128 v[224:227], v182 offset:55296
	ds_read_b128 v[228:231], v182 offset:56320
	global_load_lds_dwordx4 v[176:177], off
	s_add_i32 m0, s18, 0x2000
	s_add_u32 s18, s22, 0xb0080
	v_lshl_add_u64 v[176:177], v[232:233], 0, s[12:13]
	s_addc_u32 s19, s23, 0
	s_add_i32 s22, s57, s35
	global_load_lds_dwordx4 v[176:177], off
	s_mov_b32 m0, s22
	s_nop 0
	global_load_lds_dwordx4 v146, s[18:19]
	s_add_i32 m0, s22, 0x2000
	s_nop 0
	global_load_lds_dwordx4 v150, s[18:19]
	v_lshl_add_u64 v[176:177], v[234:235], 0, s[12:13]
	s_mov_b32 m0, s45
	s_nop 0
	global_load_lds_dwordx4 v[176:177], off
	v_lshl_add_u64 v[176:177], v[236:237], 0, s[12:13]
	s_mov_b32 m0, s46
	s_nop 0
	global_load_lds_dwordx4 v[176:177], off
	s_waitcnt vmcnt(8)
	s_waitcnt lgkmcnt(0)
	s_barrier
	s_setprio 1
	s_waitcnt lgkmcnt(0)
	v_mfma_f32_16x16x32_bf16 v[60:63], v[120:123], v[200:203], v[60:63]
	v_mfma_f32_16x16x32_bf16 v[56:59], v[136:139], v[200:203], v[56:59]
	v_mfma_f32_16x16x32_bf16 v[52:55], v[120:123], v[208:211], v[52:55]
	v_mfma_f32_16x16x32_bf16 v[40:43], v[136:139], v[208:211], v[40:43]
	v_mfma_f32_16x16x32_bf16 v[36:39], v[120:123], v[216:219], v[36:39]
	v_mfma_f32_16x16x32_bf16 v[24:27], v[136:139], v[216:219], v[24:27]
	v_mfma_f32_16x16x32_bf16 v[20:23], v[120:123], v[224:227], v[20:23]
	v_mfma_f32_16x16x32_bf16 v[8:11], v[136:139], v[224:227], v[8:11]
	v_mfma_f32_16x16x32_bf16 v[60:63], v[124:127], v[204:207], v[60:63]
	v_mfma_f32_16x16x32_bf16 v[56:59], v[140:143], v[204:207], v[56:59]
	v_mfma_f32_16x16x32_bf16 v[52:55], v[124:127], v[212:215], v[52:55]
	v_mfma_f32_16x16x32_bf16 v[40:43], v[140:143], v[212:215], v[40:43]
	v_mfma_f32_16x16x32_bf16 v[36:39], v[124:127], v[220:223], v[36:39]
	v_mfma_f32_16x16x32_bf16 v[24:27], v[140:143], v[220:223], v[24:27]
	v_mfma_f32_16x16x32_bf16 v[20:23], v[124:127], v[228:231], v[20:23]
	v_mfma_f32_16x16x32_bf16 v[8:11], v[140:143], v[228:231], v[8:11]
	v_mfma_f32_16x16x32_bf16 v[48:51], v[184:187], v[200:203], v[48:51]
	v_mfma_f32_16x16x32_bf16 v[44:47], v[192:195], v[200:203], v[44:47]
	v_mfma_f32_16x16x32_bf16 v[32:35], v[184:187], v[208:211], v[32:35]
	v_mfma_f32_16x16x32_bf16 v[28:31], v[192:195], v[208:211], v[28:31]
	v_mfma_f32_16x16x32_bf16 v[16:19], v[184:187], v[216:219], v[16:19]
	v_mfma_f32_16x16x32_bf16 v[12:15], v[192:195], v[216:219], v[12:15]
	v_mfma_f32_16x16x32_bf16 v[4:7], v[184:187], v[224:227], v[4:7]
	v_mfma_f32_16x16x32_bf16 v[0:3], v[192:195], v[224:227], v[0:3]
	v_mfma_f32_16x16x32_bf16 v[48:51], v[188:191], v[204:207], v[48:51]
	v_mfma_f32_16x16x32_bf16 v[44:47], v[196:199], v[204:207], v[44:47]
	v_mfma_f32_16x16x32_bf16 v[32:35], v[188:191], v[212:215], v[32:35]
	v_mfma_f32_16x16x32_bf16 v[28:31], v[196:199], v[212:215], v[28:31]
	v_mfma_f32_16x16x32_bf16 v[16:19], v[188:191], v[220:223], v[16:19]
	v_mfma_f32_16x16x32_bf16 v[12:15], v[196:199], v[220:223], v[12:15]
	v_mfma_f32_16x16x32_bf16 v[4:7], v[188:191], v[228:231], v[4:7]
	v_mfma_f32_16x16x32_bf16 v[0:3], v[196:199], v[228:231], v[0:3]
	s_setprio 0
	s_barrier
	s_add_i32 s55, s55, 2
	s_add_u32 s33, s33, 0x100
	s_addc_u32 s54, s54, 0
	s_cmp_gt_u32 s55, 41
	s_mov_b64 s[18:19], s[20:21]
	s_cbranch_scc0 .LBB0_989
	s_and_b64 vcc, exec, s[14:15]
	s_cbranch_vccz .LBB0_992
	s_barrier

; #define PG8_STAGE(bufoff, gbase, voff) do { _Pragma("unroll") for (int _i = 0; _i < 2; ++_i) \
;         __builtin_amdgcn_global_load_lds((const unsigned*)((const char*)(gbase) + (voff)[_i]), (PG8_LAS unsigned*)(lds + (bufoff) + ldsw + _i * 8192), 16, 0, 0); } while (0)
; #define PG8_LDA(dst, b, h) do { _Pragma("unroll") for (int m = 0; m < 4; ++m) _Pragma("unroll") for (int k = 0; k < 2; ++k) dst[m][k] = *(const PG8_LAS bf16x8*)(lds + PG8_SA(b, h) + aoff + m * 2048 + k * 1024); } while (0)
; #define PG8_LDB(dst, b, h) do { _Pragma("unroll") for (int n = 0; n < 2; ++n) _Pragma("unroll") for (int k = 0; k < 2; ++k) dst[n][k] = *(const PG8_LAS bf16x8*)(lds + PG8_SB(b, h) + boff + n * 2048 + k * 1024); } while (0)
; #define PG8_MMA(ai, bj, At, Bt) do { __builtin_amdgcn_s_setprio(1); _Pragma("unroll") for (int m = 0; m < 4; ++m) _Pragma("unroll") for (int n = 0; n < 2; ++n) _Pragma("unroll") for (int k = 0; k < 2; ++k) \
;         acc[ai][bj][m][n] = __builtin_amdgcn_mfma_f32_16x16x32_bf16(Bt[n][k], At[m][k], acc[ai][bj][m][n], 0, 0, 0); __builtin_amdgcn_s_setprio(0); } while (0)
; #define PG8_WAIT_V(n) asm volatile("s_waitcnt vmcnt(" #n ")" ::: "memory")
; #define PG8_WAIT_L(n) asm volatile("s_waitcnt lgkmcnt(" #n ")" ::: "memory")
; #define PG8_BAR __builtin_amdgcn_s_barrier()
; #define PG8_SCHED __builtin_amdgcn_sched_barrier(0)
; template <class Epi, class Sched, bool ALIGN_EPI = false, bool SP2 = false>
; __device__ __forceinline__ void gemm_phase(PG8_LAS unsigned char* lds, const Gemm g, const Sched& S, const Epi& E, const int tid) {
;     ...
;             PG8_LDB(B0, 0, 0); PG8_LDB(B1, 0, 1); PG8_SCHED; PG8_LDA(At, 0, 0); PG8_STAGE(PG8_SA(1, 1), a1 + hstep, voffA);
;             PG8_WAIT_V(8); PG8_WAIT_L(0); PG8_BAR; PG8_MMA(0, 0, At, B0); PG8_MMA(0, 1, At, B1); PG8_BAR; PG8_SCHED;
;             PG8_LDA(At, 0, 1); PG8_STAGE(PG8_SB(0, 0), b2, voffB); PG8_STAGE(PG8_SB(0, 1), b2 + hstep, voffB); PG8_STAGE(PG8_SA(0, 0), a2, voffA);
;             PG8_WAIT_V(8); PG8_WAIT_L(0); PG8_BAR; PG8_MMA(1, 0, At, B0); PG8_MMA(1, 1, At, B1); PG8_BAR; PG8_SCHED;
.LBB0_1575:
	ds_read_b128 v[120:123], v180
	ds_read_b128 v[124:127], v180 offset:1024
	ds_read_b128 v[136:139], v180 offset:2048
	ds_read_b128 v[140:143], v180 offset:3072
	ds_read_b128 v[184:187], v181
	ds_read_b128 v[188:191], v181 offset:1024
	ds_read_b128 v[192:195], v181 offset:2048
	ds_read_b128 v[196:199], v181 offset:3072
	s_add_u32 s24, s22, 0xfffc0080
	s_addc_u32 s25, s23, -1
	s_cmp_eq_u32 s57, 12
	s_cselect_b32 s27, s15, s25
	s_cselect_b32 s26, s21, s24
	s_cselect_b32 s25, s13, s56
	s_cselect_b32 s24, s33, s55
	s_add_i32 m0, s38, 0xc000
	ds_read_b128 v[200:203], v182
	ds_read_b128 v[204:207], v182 offset:1024
	ds_read_b128 v[208:211], v182 offset:2048
	ds_read_b128 v[212:215], v182 offset:3072
	ds_read_b128 v[216:219], v182 offset:4096
	ds_read_b128 v[220:223], v182 offset:5120
	ds_read_b128 v[224:227], v182 offset:6144
	ds_read_b128 v[228:231], v182 offset:7168
	global_load_lds_dwordx4 v168, s[22:23]
	s_add_i32 m0, s38, 0xe000
	s_nop 0
	global_load_lds_dwordx4 v170, s[22:23]
	s_waitcnt vmcnt(8)
	s_waitcnt lgkmcnt(0)
	s_barrier
	s_setprio 1
	s_waitcnt lgkmcnt(0)
	v_mfma_f32_16x16x32_bf16 v[132:135], v[120:123], v[200:203], v[132:135]
	v_mfma_f32_16x16x32_bf16 v[128:131], v[136:139], v[200:203], v[128:131]
	v_mfma_f32_16x16x32_bf16 v[116:119], v[120:123], v[208:211], v[116:119]
	v_mfma_f32_16x16x32_bf16 v[104:107], v[136:139], v[208:211], v[104:107]
	v_mfma_f32_16x16x32_bf16 v[100:103], v[120:123], v[216:219], v[100:103]
	v_mfma_f32_16x16x32_bf16 v[88:91], v[136:139], v[216:219], v[88:91]
	v_mfma_f32_16x16x32_bf16 v[84:87], v[120:123], v[224:227], v[84:87]
	v_mfma_f32_16x16x32_bf16 v[72:75], v[136:139], v[224:227], v[72:75]
	v_mfma_f32_16x16x32_bf16 v[132:135], v[124:127], v[204:207], v[132:135]
	v_mfma_f32_16x16x32_bf16 v[128:131], v[140:143], v[204:207], v[128:131]
	v_mfma_f32_16x16x32_bf16 v[116:119], v[124:127], v[212:215], v[116:119]
	v_mfma_f32_16x16x32_bf16 v[104:107], v[140:143], v[212:215], v[104:107]
	v_mfma_f32_16x16x32_bf16 v[100:103], v[124:127], v[220:223], v[100:103]
	v_mfma_f32_16x16x32_bf16 v[88:91], v[140:143], v[220:223], v[88:91]
	v_mfma_f32_16x16x32_bf16 v[84:87], v[124:127], v[228:231], v[84:87]
	v_mfma_f32_16x16x32_bf16 v[72:75], v[140:143], v[228:231], v[72:75]
	v_mfma_f32_16x16x32_bf16 v[112:115], v[184:187], v[200:203], v[112:115]
	v_mfma_f32_16x16x32_bf16 v[108:111], v[192:195], v[200:203], v[108:111]
	v_mfma_f32_16x16x32_bf16 v[96:99], v[184:187], v[208:211], v[96:99]
	v_mfma_f32_16x16x32_bf16 v[92:95], v[192:195], v[208:211], v[92:95]
	v_mfma_f32_16x16x32_bf16 v[80:83], v[184:187], v[216:219], v[80:83]
	v_mfma_f32_16x16x32_bf16 v[76:79], v[192:195], v[216:219], v[76:79]
	v_mfma_f32_16x16x32_bf16 v[68:71], v[184:187], v[224:227], v[68:71]
	v_mfma_f32_16x16x32_bf16 v[64:67], v[192:195], v[224:227], v[64:67]
	v_mfma_f32_16x16x32_bf16 v[112:115], v[188:191], v[204:207], v[112:115]
	v_mfma_f32_16x16x32_bf16 v[108:111], v[196:199], v[204:207], v[108:111]
	v_mfma_f32_16x16x32_bf16 v[96:99], v[188:191], v[212:215], v[96:99]
	v_mfma_f32_16x16x32_bf16 v[92:95], v[196:199], v[212:215], v[92:95]
	v_mfma_f32_16x16x32_bf16 v[80:83], v[188:191], v[220:223], v[80:83]
	v_mfma_f32_16x16x32_bf16 v[76:79], v[196:199], v[220:223], v[76:79]
	v_mfma_f32_16x16x32_bf16 v[68:71], v[188:191], v[228:231], v[68:71]
	v_mfma_f32_16x16x32_bf16 v[64:67], v[196:199], v[228:231], v[64:67]
	s_setprio 0
	s_barrier
	s_add_i32 s58, s52, s37
	v_lshl_add_u64 v[176:177], s[24:25], 0, v[146:147]
	s_mov_b32 m0, s58
	ds_read_b128 v[200:203], v182 offset:16384
	ds_read_b128 v[204:207], v182 offset:17408
	ds_read_b128 v[208:211], v182 offset:18432
	ds_read_b128 v[212:215], v182 offset:19456
	ds_read_b128 v[216:219], v182 offset:20480
	ds_read_b128 v[220:223], v182 offset:21504
	ds_read_b128 v[224:227], v182 offset:22528
	ds_read_b128 v[228:231], v182 offset:23552
	global_load_lds_dwordx4 v[176:177], off
	s_add_i32 m0, s58, 0x2000
	s_add_u32 s58, s24, 0x40000
	v_lshl_add_u64 v[232:233], s[24:25], 0, v[150:151]
	s_addc_u32 s59, s25, 0
	s_add_i32 s60, s53, s37
	global_load_lds_dwordx4 v[232:233], off
	s_mov_b32 m0, s60
	v_lshl_add_u64 v[236:237], s[26:27], 0, v[148:149]
	global_load_lds_dwordx4 v146, s[58:59]
	s_add_i32 m0, s60, 0x2000
	s_nop 0
	global_load_lds_dwordx4 v150, s[58:59]
	v_lshl_add_u64 v[234:235], s[26:27], 0, v[144:145]
	s_mov_b32 m0, s38
	s_nop 0
	global_load_lds_dwordx4 v[234:235], off
	s_mov_b32 m0, s39
	s_nop 0
	global_load_lds_dwordx4 v[236:237], off
	s_waitcnt vmcnt(8)
	s_waitcnt lgkmcnt(0)
	s_barrier
	s_setprio 1
	s_waitcnt lgkmcnt(0)
	v_mfma_f32_16x16x32_bf16 v[60:63], v[120:123], v[200:203], v[60:63]
	v_mfma_f32_16x16x32_bf16 v[56:59], v[136:139], v[200:203], v[56:59]
	v_mfma_f32_16x16x32_bf16 v[52:55], v[120:123], v[208:211], v[52:55]
	v_mfma_f32_16x16x32_bf16 v[40:43], v[136:139], v[208:211], v[40:43]
	v_mfma_f32_16x16x32_bf16 v[36:39], v[120:123], v[216:219], v[36:39]
	v_mfma_f32_16x16x32_bf16 v[24:27], v[136:139], v[216:219], v[24:27]
	v_mfma_f32_16x16x32_bf16 v[20:23], v[120:123], v[224:227], v[20:23]
	v_mfma_f32_16x16x32_bf16 v[8:11], v[136:139], v[224:227], v[8:11]
	v_mfma_f32_16x16x32_bf16 v[60:63], v[124:127], v[204:207], v[60:63]
	v_mfma_f32_16x16x32_bf16 v[56:59], v[140:143], v[204:207], v[56:59]
	v_mfma_f32_16x16x32_bf16 v[52:55], v[124:127], v[212:215], v[52:55]
	v_mfma_f32_16x16x32_bf16 v[40:43], v[140:143], v[212:215], v[40:43]
	v_mfma_f32_16x16x32_bf16 v[36:39], v[124:127], v[220:223], v[36:39]
	v_mfma_f32_16x16x32_bf16 v[24:27], v[140:143], v[220:223], v[24:27]
	v_mfma_f32_16x16x32_bf16 v[20:23], v[124:127], v[228:231], v[20:23]
	v_mfma_f32_16x16x32_bf16 v[8:11], v[140:143], v[228:231], v[8:11]
	v_mfma_f32_16x16x32_bf16 v[48:51], v[184:187], v[200:203], v[48:51]
	v_mfma_f32_16x16x32_bf16 v[44:47], v[192:195], v[200:203], v[44:47]
	v_mfma_f32_16x16x32_bf16 v[32:35], v[184:187], v[208:211], v[32:35]
	v_mfma_f32_16x16x32_bf16 v[28:31], v[192:195], v[208:211], v[28:31]
	v_mfma_f32_16x16x32_bf16 v[16:19], v[184:187], v[216:219], v[16:19]
	v_mfma_f32_16x16x32_bf16 v[12:15], v[192:195], v[216:219], v[12:15]
	v_mfma_f32_16x16x32_bf16 v[4:7], v[184:187], v[224:227], v[4:7]
	v_mfma_f32_16x16x32_bf16 v[0:3], v[192:195], v[224:227], v[0:3]
	v_mfma_f32_16x16x32_bf16 v[48:51], v[188:191], v[204:207], v[48:51]
	v_mfma_f32_16x16x32_bf16 v[44:47], v[196:199], v[204:207], v[44:47]
	v_mfma_f32_16x16x32_bf16 v[32:35], v[188:191], v[212:215], v[32:35]
	v_mfma_f32_16x16x32_bf16 v[28:31], v[196:199], v[212:215], v[28:31]
	v_mfma_f32_16x16x32_bf16 v[16:19], v[188:191], v[220:223], v[16:19]
	v_mfma_f32_16x16x32_bf16 v[12:15], v[196:199], v[220:223], v[12:15]
	v_mfma_f32_16x16x32_bf16 v[4:7], v[188:191], v[228:231], v[4:7]
	v_mfma_f32_16x16x32_bf16 v[0:3], v[196:199], v[228:231], v[0:3]
	s_setprio 0
	s_barrier
; #define PG8_STAGE(bufoff, gbase, voff) do { _Pragma("unroll") for (int _i = 0; _i < 2; ++_i) \
;         __builtin_amdgcn_global_load_lds((const unsigned*)((const char*)(gbase) + (voff)[_i]), (PG8_LAS unsigned*)(lds + (bufoff) + ldsw + _i * 8192), 16, 0, 0); } while (0)
; #define PG8_LDA(dst, b, h) do { _Pragma("unroll") for (int m = 0; m < 4; ++m) _Pragma("unroll") for (int k = 0; k < 2; ++k) dst[m][k] = *(const PG8_LAS bf16x8*)(lds + PG8_SA(b, h) + aoff + m * 2048 + k * 1024); } while (0)
; #define PG8_LDB(dst, b, h) do { _Pragma("unroll") for (int n = 0; n < 2; ++n) _Pragma("unroll") for (int k = 0; k < 2; ++k) dst[n][k] = *(const PG8_LAS bf16x8*)(lds + PG8_SB(b, h) + boff + n * 2048 + k * 1024); } while (0)
; #define PG8_MMA(ai, bj, At, Bt) do { __builtin_amdgcn_s_setprio(1); _Pragma("unroll") for (int m = 0; m < 4; ++m) _Pragma("unroll") for (int n = 0; n < 2; ++n) _Pragma("unroll") for (int k = 0; k < 2; ++k) \
;         acc[ai][bj][m][n] = __builtin_amdgcn_mfma_f32_16x16x32_bf16(Bt[n][k], At[m][k], acc[ai][bj][m][n], 0, 0, 0); __builtin_amdgcn_s_setprio(0); } while (0)
; #define PG8_WAIT_V(n) asm volatile("s_waitcnt vmcnt(" #n ")" ::: "memory")
; #define PG8_WAIT_L(n) asm volatile("s_waitcnt lgkmcnt(" #n ")" ::: "memory")
; #define PG8_BAR __builtin_amdgcn_s_barrier()
; #define PG8_SCHED __builtin_amdgcn_sched_barrier(0)
; template <class Epi, class Sched, bool ALIGN_EPI = false, bool SP2 = false>
; __device__ __forceinline__ void gemm_phase(PG8_LAS unsigned char* lds, const Gemm g, const Sched& S, const Epi& E, const int tid) {
;     ...
;             PG8_LDB(B0, 1, 0); PG8_LDB(B1, 1, 1); PG8_SCHED; PG8_LDA(At, 1, 0); PG8_STAGE(PG8_SA(0, 1), a2 + hstep, voffA);
;             PG8_WAIT_V(8); PG8_WAIT_L(0); PG8_BAR; PG8_MMA(0, 0, At, B0); PG8_MMA(0, 1, At, B1); PG8_BAR; PG8_SCHED;
;             PG8_LDA(At, 1, 1); PG8_STAGE(PG8_SB(1, 0), b3, voffB); PG8_STAGE(PG8_SB(1, 1), b3 + hstep, voffB); PG8_STAGE(PG8_SA(1, 0), a3, voffA);
;             PG8_WAIT_V(8); PG8_WAIT_L(0); PG8_BAR; PG8_MMA(1, 0, At, B0); PG8_MMA(1, 1, At, B1); PG8_BAR; PG8_SCHED;
	s_add_i32 s58, 0, 0x18000
	s_add_i32 s59, 0, 0x1c000
	v_add_u32_e32 v140, s58, v178
	v_add_u32_e32 v183, s59, v178
	ds_read_b128 v[120:123], v140
	ds_read_b128 v[124:127], v140 offset:1024
	ds_read_b128 v[136:139], v140 offset:2048
	ds_read_b128 v[140:143], v140 offset:3072
	ds_read_b128 v[184:187], v183
	ds_read_b128 v[188:191], v183 offset:1024
	ds_read_b128 v[192:195], v183 offset:2048
	ds_read_b128 v[196:199], v183 offset:3072
	s_add_u32 s26, s26, 0x40000
	s_addc_u32 s27, s27, 0
	s_mov_b32 m0, s40
	ds_read_b128 v[200:203], v182 offset:32768
	ds_read_b128 v[204:207], v182 offset:33792
	ds_read_b128 v[208:211], v182 offset:34816
	ds_read_b128 v[212:215], v182 offset:35840
	ds_read_b128 v[216:219], v182 offset:36864
	ds_read_b128 v[220:223], v182 offset:37888
	ds_read_b128 v[224:227], v182 offset:38912
	ds_read_b128 v[228:231], v182 offset:39936
	global_load_lds_dwordx4 v144, s[26:27]
	v_lshl_add_u64 v[238:239], s[26:27], 0, v[148:149]
	s_mov_b32 m0, s41
	s_nop 0
	global_load_lds_dwordx4 v[238:239], off
	s_waitcnt vmcnt(8)
	s_waitcnt lgkmcnt(0)
	s_barrier
	s_setprio 1
	s_waitcnt lgkmcnt(0)
	v_mfma_f32_16x16x32_bf16 v[132:135], v[120:123], v[200:203], v[132:135]
	v_mfma_f32_16x16x32_bf16 v[128:131], v[136:139], v[200:203], v[128:131]
	v_mfma_f32_16x16x32_bf16 v[116:119], v[120:123], v[208:211], v[116:119]
	v_mfma_f32_16x16x32_bf16 v[104:107], v[136:139], v[208:211], v[104:107]
	v_mfma_f32_16x16x32_bf16 v[100:103], v[120:123], v[216:219], v[100:103]
	v_mfma_f32_16x16x32_bf16 v[88:91], v[136:139], v[216:219], v[88:91]
	v_mfma_f32_16x16x32_bf16 v[84:87], v[120:123], v[224:227], v[84:87]
	v_mfma_f32_16x16x32_bf16 v[72:75], v[136:139], v[224:227], v[72:75]
	v_mfma_f32_16x16x32_bf16 v[132:135], v[124:127], v[204:207], v[132:135]
	v_mfma_f32_16x16x32_bf16 v[128:131], v[140:143], v[204:207], v[128:131]
	v_mfma_f32_16x16x32_bf16 v[116:119], v[124:127], v[212:215], v[116:119]
	v_mfma_f32_16x16x32_bf16 v[104:107], v[140:143], v[212:215], v[104:107]
	v_mfma_f32_16x16x32_bf16 v[100:103], v[124:127], v[220:223], v[100:103]
	v_mfma_f32_16x16x32_bf16 v[88:91], v[140:143], v[220:223], v[88:91]
	v_mfma_f32_16x16x32_bf16 v[84:87], v[124:127], v[228:231], v[84:87]
	v_mfma_f32_16x16x32_bf16 v[72:75], v[140:143], v[228:231], v[72:75]
	v_mfma_f32_16x16x32_bf16 v[112:115], v[184:187], v[200:203], v[112:115]
	v_mfma_f32_16x16x32_bf16 v[108:111], v[192:195], v[200:203], v[108:111]
	v_mfma_f32_16x16x32_bf16 v[96:99], v[184:187], v[208:211], v[96:99]
	v_mfma_f32_16x16x32_bf16 v[92:95], v[192:195], v[208:211], v[92:95]
	v_mfma_f32_16x16x32_bf16 v[80:83], v[184:187], v[216:219], v[80:83]
	v_mfma_f32_16x16x32_bf16 v[76:79], v[192:195], v[216:219], v[76:79]
	v_mfma_f32_16x16x32_bf16 v[68:71], v[184:187], v[224:227], v[68:71]
	v_mfma_f32_16x16x32_bf16 v[64:67], v[192:195], v[224:227], v[64:67]
	v_mfma_f32_16x16x32_bf16 v[112:115], v[188:191], v[204:207], v[112:115]
	v_mfma_f32_16x16x32_bf16 v[108:111], v[196:199], v[204:207], v[108:111]
	v_mfma_f32_16x16x32_bf16 v[96:99], v[188:191], v[212:215], v[96:99]
	v_mfma_f32_16x16x32_bf16 v[92:95], v[196:199], v[212:215], v[92:95]
	v_mfma_f32_16x16x32_bf16 v[80:83], v[188:191], v[220:223], v[80:83]
	v_mfma_f32_16x16x32_bf16 v[76:79], v[196:199], v[220:223], v[76:79]
	v_mfma_f32_16x16x32_bf16 v[68:71], v[188:191], v[228:231], v[68:71]
	v_mfma_f32_16x16x32_bf16 v[64:67], v[196:199], v[228:231], v[64:67]
	s_setprio 0
	s_barrier
	s_add_i32 s26, s58, s37
	v_lshl_add_u64 v[176:177], v[176:177], 0, s[6:7]
	s_mov_b32 m0, s26
	ds_read_b128 v[200:203], v182 offset:49152
	ds_read_b128 v[204:207], v182 offset:50176
	ds_read_b128 v[208:211], v182 offset:51200
	ds_read_b128 v[212:215], v182 offset:52224
	ds_read_b128 v[216:219], v182 offset:53248
	ds_read_b128 v[220:223], v182 offset:54272
	ds_read_b128 v[224:227], v182 offset:55296
	ds_read_b128 v[228:231], v182 offset:56320
	global_load_lds_dwordx4 v[176:177], off
	s_add_i32 m0, s26, 0x2000
	s_add_u32 s24, s24, 0x40080
	v_lshl_add_u64 v[176:177], v[232:233], 0, s[6:7]
	s_addc_u32 s25, s25, 0
	s_add_i32 s26, s59, s37
	global_load_lds_dwordx4 v[176:177], off
	s_mov_b32 m0, s26
	s_nop 0
	global_load_lds_dwordx4 v146, s[24:25]
	s_add_i32 m0, s26, 0x2000
	s_nop 0
	global_load_lds_dwordx4 v150, s[24:25]
	v_lshl_add_u64 v[176:177], v[234:235], 0, s[6:7]
	s_mov_b32 m0, s49
	s_nop 0
	global_load_lds_dwordx4 v[176:177], off
	v_lshl_add_u64 v[176:177], v[236:237], 0, s[6:7]
	s_mov_b32 m0, s50
	s_nop 0
	global_load_lds_dwordx4 v[176:177], off
	s_waitcnt vmcnt(8)
	s_waitcnt lgkmcnt(0)
	s_barrier
	s_setprio 1
	s_waitcnt lgkmcnt(0)
	v_mfma_f32_16x16x32_bf16 v[60:63], v[120:123], v[200:203], v[60:63]
	v_mfma_f32_16x16x32_bf16 v[56:59], v[136:139], v[200:203], v[56:59]
	v_mfma_f32_16x16x32_bf16 v[52:55], v[120:123], v[208:211], v[52:55]
	v_mfma_f32_16x16x32_bf16 v[40:43], v[136:139], v[208:211], v[40:43]
	v_mfma_f32_16x16x32_bf16 v[36:39], v[120:123], v[216:219], v[36:39]
	v_mfma_f32_16x16x32_bf16 v[24:27], v[136:139], v[216:219], v[24:27]
	v_mfma_f32_16x16x32_bf16 v[20:23], v[120:123], v[224:227], v[20:23]
	v_mfma_f32_16x16x32_bf16 v[8:11], v[136:139], v[224:227], v[8:11]
	v_mfma_f32_16x16x32_bf16 v[60:63], v[124:127], v[204:207], v[60:63]
	v_mfma_f32_16x16x32_bf16 v[56:59], v[140:143], v[204:207], v[56:59]
	v_mfma_f32_16x16x32_bf16 v[52:55], v[124:127], v[212:215], v[52:55]
	v_mfma_f32_16x16x32_bf16 v[40:43], v[140:143], v[212:215], v[40:43]
	v_mfma_f32_16x16x32_bf16 v[36:39], v[124:127], v[220:223], v[36:39]
	v_mfma_f32_16x16x32_bf16 v[24:27], v[140:143], v[220:223], v[24:27]
	v_mfma_f32_16x16x32_bf16 v[20:23], v[124:127], v[228:231], v[20:23]
	v_mfma_f32_16x16x32_bf16 v[8:11], v[140:143], v[228:231], v[8:11]
	v_mfma_f32_16x16x32_bf16 v[48:51], v[184:187], v[200:203], v[48:51]
	v_mfma_f32_16x16x32_bf16 v[44:47], v[192:195], v[200:203], v[44:47]
	v_mfma_f32_16x16x32_bf16 v[32:35], v[184:187], v[208:211], v[32:35]
	v_mfma_f32_16x16x32_bf16 v[28:31], v[192:195], v[208:211], v[28:31]
	v_mfma_f32_16x16x32_bf16 v[16:19], v[184:187], v[216:219], v[16:19]
	v_mfma_f32_16x16x32_bf16 v[12:15], v[192:195], v[216:219], v[12:15]
	v_mfma_f32_16x16x32_bf16 v[4:7], v[184:187], v[224:227], v[4:7]
	v_mfma_f32_16x16x32_bf16 v[0:3], v[192:195], v[224:227], v[0:3]
	v_mfma_f32_16x16x32_bf16 v[48:51], v[188:191], v[204:207], v[48:51]
	v_mfma_f32_16x16x32_bf16 v[44:47], v[196:199], v[204:207], v[44:47]
	v_mfma_f32_16x16x32_bf16 v[32:35], v[188:191], v[212:215], v[32:35]
	v_mfma_f32_16x16x32_bf16 v[28:31], v[196:199], v[212:215], v[28:31]
	v_mfma_f32_16x16x32_bf16 v[16:19], v[188:191], v[220:223], v[16:19]
	v_mfma_f32_16x16x32_bf16 v[12:15], v[196:199], v[220:223], v[12:15]
	v_mfma_f32_16x16x32_bf16 v[4:7], v[188:191], v[228:231], v[4:7]
	v_mfma_f32_16x16x32_bf16 v[0:3], v[196:199], v[228:231], v[0:3]
	s_setprio 0
	s_barrier
	s_add_i32 s57, s57, 2
	s_add_u32 s22, s22, 0x100
	s_addc_u32 s23, s23, 0
	s_add_u32 s55, s55, 0x100
	s_addc_u32 s56, s56, 0
	s_cmp_gt_u32 s57, 13
	s_cbranch_scc0 .LBB0_1575
	s_and_b64 vcc, exec, s[8:9]
	s_cbranch_vccz .LBB0_1578
	s_barrier

; #define PG8_STAGE(bufoff, gbase, voff) do { _Pragma("unroll") for (int _i = 0; _i < 2; ++_i) \
;         __builtin_amdgcn_global_load_lds((const unsigned*)((const char*)(gbase) + (voff)[_i]), (PG8_LAS unsigned*)(lds + (bufoff) + ldsw + _i * 8192), 16, 0, 0); } while (0)
; #define PG8_LDA(dst, b, h) do { _Pragma("unroll") for (int m = 0; m < 4; ++m) _Pragma("unroll") for (int k = 0; k < 2; ++k) dst[m][k] = *(const PG8_LAS bf16x8*)(lds + PG8_SA(b, h) + aoff + m * 2048 + k * 1024); } while (0)
; #define PG8_LDB(dst, b, h) do { _Pragma("unroll") for (int n = 0; n < 2; ++n) _Pragma("unroll") for (int k = 0; k < 2; ++k) dst[n][k] = *(const PG8_LAS bf16x8*)(lds + PG8_SB(b, h) + boff + n * 2048 + k * 1024); } while (0)
; #define PG8_MMA(ai, bj, At, Bt) do { __builtin_amdgcn_s_setprio(1); _Pragma("unroll") for (int m = 0; m < 4; ++m) _Pragma("unroll") for (int n = 0; n < 2; ++n) _Pragma("unroll") for (int k = 0; k < 2; ++k) \
;         acc[ai][bj][m][n] = __builtin_amdgcn_mfma_f32_16x16x32_bf16(Bt[n][k], At[m][k], acc[ai][bj][m][n], 0, 0, 0); __builtin_amdgcn_s_setprio(0); } while (0)
; #define PG8_WAIT_V(n) asm volatile("s_waitcnt vmcnt(" #n ")" ::: "memory")
; #define PG8_WAIT_L(n) asm volatile("s_waitcnt lgkmcnt(" #n ")" ::: "memory")
; #define PG8_BAR __builtin_amdgcn_s_barrier()
; #define PG8_SCHED __builtin_amdgcn_sched_barrier(0)
; template <class Epi, class Sched, bool ALIGN_EPI = false, bool SP2 = false>
; __device__ __forceinline__ void gemm_phase(PG8_LAS unsigned char* lds, const Gemm g, const Sched& S, const Epi& E, const int tid) {
;     ...
;             PG8_LDB(B0, 0, 0); PG8_LDB(B1, 0, 1); PG8_SCHED; PG8_LDA(At, 0, 0); PG8_STAGE(PG8_SA(1, 1), a1 + hstep, voffA);
;             PG8_WAIT_V(8); PG8_WAIT_L(0); PG8_BAR; PG8_MMA(0, 0, At, B0); PG8_MMA(0, 1, At, B1); PG8_BAR; PG8_SCHED;
;             PG8_LDA(At, 0, 1); PG8_STAGE(PG8_SB(0, 0), b2, voffB); PG8_STAGE(PG8_SB(0, 1), b2 + hstep, voffB); PG8_STAGE(PG8_SA(0, 0), a2, voffA);
;             PG8_WAIT_V(8); PG8_WAIT_L(0); PG8_BAR; PG8_MMA(1, 0, At, B0); PG8_MMA(1, 1, At, B1); PG8_BAR; PG8_SCHED;
.LBB0_1704:
	ds_read_b128 v[150:153], v147
	ds_read_b128 v[154:157], v147 offset:1024
	ds_read_b128 v[158:161], v147 offset:2048
	ds_read_b128 v[162:165], v147 offset:3072
	ds_read_b128 v[166:169], v148
	ds_read_b128 v[170:173], v148 offset:1024
	ds_read_b128 v[174:177], v148 offset:2048
	ds_read_b128 v[178:181], v148 offset:3072
	s_add_u32 s22, s20, 0xfffc0080
	s_addc_u32 s23, s21, -1
	s_cmp_eq_u32 s53, 12
	s_cselect_b32 s25, s33, s23
	s_cselect_b32 s24, s49, s22
	s_cselect_b32 s23, s13, s52
	s_cselect_b32 s22, s50, s51
	s_add_i32 m0, s19, 0xc000
	ds_read_b128 v[182:185], v149
	ds_read_b128 v[186:189], v149 offset:1024
	ds_read_b128 v[190:193], v149 offset:2048
	ds_read_b128 v[194:197], v149 offset:3072
	ds_read_b128 v[198:201], v149 offset:4096
	ds_read_b128 v[202:205], v149 offset:5120
	ds_read_b128 v[206:209], v149 offset:6144
	ds_read_b128 v[210:213], v149 offset:7168
	global_load_lds_dwordx4 v136, s[20:21]
	s_add_i32 m0, s19, 0xe000
	s_nop 0
	global_load_lds_dwordx4 v138, s[20:21]
	s_waitcnt vmcnt(8)
	s_waitcnt lgkmcnt(0)
	s_barrier
	s_setprio 1
	s_waitcnt lgkmcnt(0)
	v_mfma_f32_16x16x32_bf16 v[124:127], v[150:153], v[182:185], v[124:127]
	v_mfma_f32_16x16x32_bf16 v[116:119], v[158:161], v[182:185], v[116:119]
	v_mfma_f32_16x16x32_bf16 v[108:111], v[150:153], v[190:193], v[108:111]
	v_mfma_f32_16x16x32_bf16 v[100:103], v[158:161], v[190:193], v[100:103]
	v_mfma_f32_16x16x32_bf16 v[92:95], v[150:153], v[198:201], v[92:95]
	v_mfma_f32_16x16x32_bf16 v[84:87], v[158:161], v[198:201], v[84:87]
	v_mfma_f32_16x16x32_bf16 v[76:79], v[150:153], v[206:209], v[76:79]
	v_mfma_f32_16x16x32_bf16 v[68:71], v[158:161], v[206:209], v[68:71]
	v_mfma_f32_16x16x32_bf16 v[124:127], v[154:157], v[186:189], v[124:127]
	v_mfma_f32_16x16x32_bf16 v[116:119], v[162:165], v[186:189], v[116:119]
	v_mfma_f32_16x16x32_bf16 v[108:111], v[154:157], v[194:197], v[108:111]
	v_mfma_f32_16x16x32_bf16 v[100:103], v[162:165], v[194:197], v[100:103]
	v_mfma_f32_16x16x32_bf16 v[92:95], v[154:157], v[202:205], v[92:95]
	v_mfma_f32_16x16x32_bf16 v[84:87], v[162:165], v[202:205], v[84:87]
	v_mfma_f32_16x16x32_bf16 v[76:79], v[154:157], v[210:213], v[76:79]
	v_mfma_f32_16x16x32_bf16 v[68:71], v[162:165], v[210:213], v[68:71]
	v_mfma_f32_16x16x32_bf16 v[120:123], v[166:169], v[182:185], v[120:123]
	v_mfma_f32_16x16x32_bf16 v[112:115], v[174:177], v[182:185], v[112:115]
	v_mfma_f32_16x16x32_bf16 v[104:107], v[166:169], v[190:193], v[104:107]
	v_mfma_f32_16x16x32_bf16 v[96:99], v[174:177], v[190:193], v[96:99]
	v_mfma_f32_16x16x32_bf16 v[88:91], v[166:169], v[198:201], v[88:91]
	v_mfma_f32_16x16x32_bf16 v[80:83], v[174:177], v[198:201], v[80:83]
	v_mfma_f32_16x16x32_bf16 v[72:75], v[166:169], v[206:209], v[72:75]
	v_mfma_f32_16x16x32_bf16 v[64:67], v[174:177], v[206:209], v[64:67]
	v_mfma_f32_16x16x32_bf16 v[120:123], v[170:173], v[186:189], v[120:123]
	v_mfma_f32_16x16x32_bf16 v[112:115], v[178:181], v[186:189], v[112:115]
	v_mfma_f32_16x16x32_bf16 v[104:107], v[170:173], v[194:197], v[104:107]
	v_mfma_f32_16x16x32_bf16 v[96:99], v[178:181], v[194:197], v[96:99]
	v_mfma_f32_16x16x32_bf16 v[88:91], v[170:173], v[202:205], v[88:91]
	v_mfma_f32_16x16x32_bf16 v[80:83], v[178:181], v[202:205], v[80:83]
	v_mfma_f32_16x16x32_bf16 v[72:75], v[170:173], v[210:213], v[72:75]
	v_mfma_f32_16x16x32_bf16 v[64:67], v[178:181], v[210:213], v[64:67]
	s_setprio 0
	s_barrier
	s_add_i32 s54, s44, s34
	v_lshl_add_u64 v[214:215], s[22:23], 0, v[132:133]
	s_mov_b32 m0, s54
	ds_read_b128 v[182:185], v149 offset:16384
	ds_read_b128 v[186:189], v149 offset:17408
	ds_read_b128 v[190:193], v149 offset:18432
	ds_read_b128 v[194:197], v149 offset:19456
	ds_read_b128 v[198:201], v149 offset:20480
	ds_read_b128 v[202:205], v149 offset:21504
	ds_read_b128 v[206:209], v149 offset:22528
	ds_read_b128 v[210:213], v149 offset:23552
	global_load_lds_dwordx4 v[214:215], off
	s_add_i32 m0, s54, 0x2000
	s_add_u32 s54, s22, 0x40000
	v_lshl_add_u64 v[216:217], s[22:23], 0, v[128:129]
	s_addc_u32 s55, s23, 0
	s_add_i32 s56, s45, s34
	global_load_lds_dwordx4 v[216:217], off
	s_mov_b32 m0, s56
	v_lshl_add_u64 v[220:221], s[24:25], 0, v[130:131]
	global_load_lds_dwordx4 v132, s[54:55]
	s_add_i32 m0, s56, 0x2000
	s_nop 0
	global_load_lds_dwordx4 v128, s[54:55]
	v_lshl_add_u64 v[218:219], s[24:25], 0, v[134:135]
	s_mov_b32 m0, s19
	s_nop 0
	global_load_lds_dwordx4 v[218:219], off
	s_mov_b32 m0, s37
	s_nop 0
	global_load_lds_dwordx4 v[220:221], off
	s_waitcnt vmcnt(8)
	s_waitcnt lgkmcnt(0)
	s_barrier
	s_setprio 1
	s_waitcnt lgkmcnt(0)
	v_mfma_f32_16x16x32_bf16 v[60:63], v[150:153], v[182:185], v[60:63]
	v_mfma_f32_16x16x32_bf16 v[52:55], v[158:161], v[182:185], v[52:55]
	v_mfma_f32_16x16x32_bf16 v[44:47], v[150:153], v[190:193], v[44:47]
	v_mfma_f32_16x16x32_bf16 v[36:39], v[158:161], v[190:193], v[36:39]
	v_mfma_f32_16x16x32_bf16 v[28:31], v[150:153], v[198:201], v[28:31]
	v_mfma_f32_16x16x32_bf16 v[20:23], v[158:161], v[198:201], v[20:23]
	v_mfma_f32_16x16x32_bf16 v[12:15], v[150:153], v[206:209], v[12:15]
	v_mfma_f32_16x16x32_bf16 v[4:7], v[158:161], v[206:209], v[4:7]
	v_mfma_f32_16x16x32_bf16 v[60:63], v[154:157], v[186:189], v[60:63]
	v_mfma_f32_16x16x32_bf16 v[52:55], v[162:165], v[186:189], v[52:55]
	v_mfma_f32_16x16x32_bf16 v[44:47], v[154:157], v[194:197], v[44:47]
	v_mfma_f32_16x16x32_bf16 v[36:39], v[162:165], v[194:197], v[36:39]
	v_mfma_f32_16x16x32_bf16 v[28:31], v[154:157], v[202:205], v[28:31]
	v_mfma_f32_16x16x32_bf16 v[20:23], v[162:165], v[202:205], v[20:23]
	v_mfma_f32_16x16x32_bf16 v[12:15], v[154:157], v[210:213], v[12:15]
	v_mfma_f32_16x16x32_bf16 v[4:7], v[162:165], v[210:213], v[4:7]
	v_mfma_f32_16x16x32_bf16 v[56:59], v[166:169], v[182:185], v[56:59]
	v_mfma_f32_16x16x32_bf16 v[48:51], v[174:177], v[182:185], v[48:51]
	v_mfma_f32_16x16x32_bf16 v[40:43], v[166:169], v[190:193], v[40:43]
	v_mfma_f32_16x16x32_bf16 v[32:35], v[174:177], v[190:193], v[32:35]
	v_mfma_f32_16x16x32_bf16 v[24:27], v[166:169], v[198:201], v[24:27]
	v_mfma_f32_16x16x32_bf16 v[16:19], v[174:177], v[198:201], v[16:19]
	v_mfma_f32_16x16x32_bf16 v[8:11], v[166:169], v[206:209], v[8:11]
	v_mfma_f32_16x16x32_bf16 v[0:3], v[174:177], v[206:209], v[0:3]
	v_mfma_f32_16x16x32_bf16 v[56:59], v[170:173], v[186:189], v[56:59]
	v_mfma_f32_16x16x32_bf16 v[48:51], v[178:181], v[186:189], v[48:51]
	v_mfma_f32_16x16x32_bf16 v[40:43], v[170:173], v[194:197], v[40:43]
	v_mfma_f32_16x16x32_bf16 v[32:35], v[178:181], v[194:197], v[32:35]
	v_mfma_f32_16x16x32_bf16 v[24:27], v[170:173], v[202:205], v[24:27]
	v_mfma_f32_16x16x32_bf16 v[16:19], v[178:181], v[202:205], v[16:19]
	v_mfma_f32_16x16x32_bf16 v[8:11], v[170:173], v[210:213], v[8:11]
	v_mfma_f32_16x16x32_bf16 v[0:3], v[178:181], v[210:213], v[0:3]
	s_setprio 0
	s_barrier
; #define PG8_STAGE(bufoff, gbase, voff) do { _Pragma("unroll") for (int _i = 0; _i < 2; ++_i) \
;         __builtin_amdgcn_global_load_lds((const unsigned*)((const char*)(gbase) + (voff)[_i]), (PG8_LAS unsigned*)(lds + (bufoff) + ldsw + _i * 8192), 16, 0, 0); } while (0)
; #define PG8_LDA(dst, b, h) do { _Pragma("unroll") for (int m = 0; m < 4; ++m) _Pragma("unroll") for (int k = 0; k < 2; ++k) dst[m][k] = *(const PG8_LAS bf16x8*)(lds + PG8_SA(b, h) + aoff + m * 2048 + k * 1024); } while (0)
; #define PG8_LDB(dst, b, h) do { _Pragma("unroll") for (int n = 0; n < 2; ++n) _Pragma("unroll") for (int k = 0; k < 2; ++k) dst[n][k] = *(const PG8_LAS bf16x8*)(lds + PG8_SB(b, h) + boff + n * 2048 + k * 1024); } while (0)
; #define PG8_MMA(ai, bj, At, Bt) do { __builtin_amdgcn_s_setprio(1); _Pragma("unroll") for (int m = 0; m < 4; ++m) _Pragma("unroll") for (int n = 0; n < 2; ++n) _Pragma("unroll") for (int k = 0; k < 2; ++k) \
;         acc[ai][bj][m][n] = __builtin_amdgcn_mfma_f32_16x16x32_bf16(Bt[n][k], At[m][k], acc[ai][bj][m][n], 0, 0, 0); __builtin_amdgcn_s_setprio(0); } while (0)
; #define PG8_WAIT_V(n) asm volatile("s_waitcnt vmcnt(" #n ")" ::: "memory")
; #define PG8_WAIT_L(n) asm volatile("s_waitcnt lgkmcnt(" #n ")" ::: "memory")
; #define PG8_BAR __builtin_amdgcn_s_barrier()
; #define PG8_SCHED __builtin_amdgcn_sched_barrier(0)
; template <class Epi, class Sched, bool ALIGN_EPI = false, bool SP2 = false>
; __device__ __forceinline__ void gemm_phase(PG8_LAS unsigned char* lds, const Gemm g, const Sched& S, const Epi& E, const int tid) {
;     ...
;             PG8_LDB(B0, 1, 0); PG8_LDB(B1, 1, 1); PG8_SCHED; PG8_LDA(At, 1, 0); PG8_STAGE(PG8_SA(0, 1), a2 + hstep, voffA);
;             PG8_WAIT_V(8); PG8_WAIT_L(0); PG8_BAR; PG8_MMA(0, 0, At, B0); PG8_MMA(0, 1, At, B1); PG8_BAR; PG8_SCHED;
;             PG8_LDA(At, 1, 1); PG8_STAGE(PG8_SB(1, 0), b3, voffB); PG8_STAGE(PG8_SB(1, 1), b3 + hstep, voffB); PG8_STAGE(PG8_SA(1, 0), a3, voffA);
;             PG8_WAIT_V(8); PG8_WAIT_L(0); PG8_BAR; PG8_MMA(1, 0, At, B0); PG8_MMA(1, 1, At, B1); PG8_BAR; PG8_SCHED;
	s_add_i32 s54, 0, 0x18000
	s_add_i32 s55, 0, 0x1c000
	v_add_u32_e32 v162, s54, v145
	v_add_u32_e32 v178, s55, v145
	ds_read_b128 v[150:153], v162
	ds_read_b128 v[154:157], v162 offset:1024
	ds_read_b128 v[158:161], v162 offset:2048
	ds_read_b128 v[162:165], v162 offset:3072
	ds_read_b128 v[166:169], v178
	ds_read_b128 v[170:173], v178 offset:1024
	ds_read_b128 v[174:177], v178 offset:2048
	ds_read_b128 v[178:181], v178 offset:3072
	s_add_u32 s24, s24, 0x40000
	s_addc_u32 s25, s25, 0
	s_mov_b32 m0, s38
	ds_read_b128 v[182:185], v149 offset:32768
	ds_read_b128 v[186:189], v149 offset:33792
	ds_read_b128 v[190:193], v149 offset:34816
	ds_read_b128 v[194:197], v149 offset:35840
	ds_read_b128 v[198:201], v149 offset:36864
	ds_read_b128 v[202:205], v149 offset:37888
	ds_read_b128 v[206:209], v149 offset:38912
	ds_read_b128 v[210:213], v149 offset:39936
	global_load_lds_dwordx4 v134, s[24:25]
	v_lshl_add_u64 v[222:223], s[24:25], 0, v[130:131]
	s_mov_b32 m0, s39
	s_nop 0
	global_load_lds_dwordx4 v[222:223], off
	s_waitcnt vmcnt(8)
	s_waitcnt lgkmcnt(0)
	s_barrier
	s_setprio 1
	s_waitcnt lgkmcnt(0)
	v_mfma_f32_16x16x32_bf16 v[124:127], v[150:153], v[182:185], v[124:127]
	v_mfma_f32_16x16x32_bf16 v[116:119], v[158:161], v[182:185], v[116:119]
	v_mfma_f32_16x16x32_bf16 v[108:111], v[150:153], v[190:193], v[108:111]
	v_mfma_f32_16x16x32_bf16 v[100:103], v[158:161], v[190:193], v[100:103]
	v_mfma_f32_16x16x32_bf16 v[92:95], v[150:153], v[198:201], v[92:95]
	v_mfma_f32_16x16x32_bf16 v[84:87], v[158:161], v[198:201], v[84:87]
	v_mfma_f32_16x16x32_bf16 v[76:79], v[150:153], v[206:209], v[76:79]
	v_mfma_f32_16x16x32_bf16 v[68:71], v[158:161], v[206:209], v[68:71]
	v_mfma_f32_16x16x32_bf16 v[124:127], v[154:157], v[186:189], v[124:127]
	v_mfma_f32_16x16x32_bf16 v[116:119], v[162:165], v[186:189], v[116:119]
	v_mfma_f32_16x16x32_bf16 v[108:111], v[154:157], v[194:197], v[108:111]
	v_mfma_f32_16x16x32_bf16 v[100:103], v[162:165], v[194:197], v[100:103]
	v_mfma_f32_16x16x32_bf16 v[92:95], v[154:157], v[202:205], v[92:95]
	v_mfma_f32_16x16x32_bf16 v[84:87], v[162:165], v[202:205], v[84:87]
	v_mfma_f32_16x16x32_bf16 v[76:79], v[154:157], v[210:213], v[76:79]
	v_mfma_f32_16x16x32_bf16 v[68:71], v[162:165], v[210:213], v[68:71]
	v_mfma_f32_16x16x32_bf16 v[120:123], v[166:169], v[182:185], v[120:123]
	v_mfma_f32_16x16x32_bf16 v[112:115], v[174:177], v[182:185], v[112:115]
	v_mfma_f32_16x16x32_bf16 v[104:107], v[166:169], v[190:193], v[104:107]
	v_mfma_f32_16x16x32_bf16 v[96:99], v[174:177], v[190:193], v[96:99]
	v_mfma_f32_16x16x32_bf16 v[88:91], v[166:169], v[198:201], v[88:91]
	v_mfma_f32_16x16x32_bf16 v[80:83], v[174:177], v[198:201], v[80:83]
	v_mfma_f32_16x16x32_bf16 v[72:75], v[166:169], v[206:209], v[72:75]
	v_mfma_f32_16x16x32_bf16 v[64:67], v[174:177], v[206:209], v[64:67]
	v_mfma_f32_16x16x32_bf16 v[120:123], v[170:173], v[186:189], v[120:123]
	v_mfma_f32_16x16x32_bf16 v[112:115], v[178:181], v[186:189], v[112:115]
	v_mfma_f32_16x16x32_bf16 v[104:107], v[170:173], v[194:197], v[104:107]
	v_mfma_f32_16x16x32_bf16 v[96:99], v[178:181], v[194:197], v[96:99]
	v_mfma_f32_16x16x32_bf16 v[88:91], v[170:173], v[202:205], v[88:91]
	v_mfma_f32_16x16x32_bf16 v[80:83], v[178:181], v[202:205], v[80:83]
	v_mfma_f32_16x16x32_bf16 v[72:75], v[170:173], v[210:213], v[72:75]
	v_mfma_f32_16x16x32_bf16 v[64:67], v[178:181], v[210:213], v[64:67]
	s_setprio 0
	s_barrier
	s_add_i32 s24, s54, s34
	v_lshl_add_u64 v[214:215], v[214:215], 0, s[8:9]
	s_mov_b32 m0, s24
	ds_read_b128 v[182:185], v149 offset:49152
	ds_read_b128 v[186:189], v149 offset:50176
	ds_read_b128 v[190:193], v149 offset:51200
	ds_read_b128 v[194:197], v149 offset:52224
	ds_read_b128 v[198:201], v149 offset:53248
	ds_read_b128 v[202:205], v149 offset:54272
	ds_read_b128 v[206:209], v149 offset:55296
	ds_read_b128 v[210:213], v149 offset:56320
	global_load_lds_dwordx4 v[214:215], off
	s_add_i32 m0, s24, 0x2000
	s_add_u32 s22, s22, 0x40080
	v_lshl_add_u64 v[214:215], v[216:217], 0, s[8:9]
	s_addc_u32 s23, s23, 0
	s_add_i32 s24, s55, s34
	global_load_lds_dwordx4 v[214:215], off
	s_mov_b32 m0, s24
	s_nop 0
	global_load_lds_dwordx4 v132, s[22:23]
	s_add_i32 m0, s24, 0x2000
	s_nop 0
	global_load_lds_dwordx4 v128, s[22:23]
	v_lshl_add_u64 v[214:215], v[218:219], 0, s[8:9]
	s_mov_b32 m0, s40
	s_nop 0
	global_load_lds_dwordx4 v[214:215], off
	v_lshl_add_u64 v[214:215], v[220:221], 0, s[8:9]
	s_mov_b32 m0, s41
	s_nop 0
	global_load_lds_dwordx4 v[214:215], off
	s_waitcnt vmcnt(8)
	s_waitcnt lgkmcnt(0)
	s_barrier
	s_setprio 1
	s_waitcnt lgkmcnt(0)
	v_mfma_f32_16x16x32_bf16 v[60:63], v[150:153], v[182:185], v[60:63]
	v_mfma_f32_16x16x32_bf16 v[52:55], v[158:161], v[182:185], v[52:55]
	v_mfma_f32_16x16x32_bf16 v[44:47], v[150:153], v[190:193], v[44:47]
	v_mfma_f32_16x16x32_bf16 v[36:39], v[158:161], v[190:193], v[36:39]
	v_mfma_f32_16x16x32_bf16 v[28:31], v[150:153], v[198:201], v[28:31]
	v_mfma_f32_16x16x32_bf16 v[20:23], v[158:161], v[198:201], v[20:23]
	v_mfma_f32_16x16x32_bf16 v[12:15], v[150:153], v[206:209], v[12:15]
	v_mfma_f32_16x16x32_bf16 v[4:7], v[158:161], v[206:209], v[4:7]
	v_mfma_f32_16x16x32_bf16 v[60:63], v[154:157], v[186:189], v[60:63]
	v_mfma_f32_16x16x32_bf16 v[52:55], v[162:165], v[186:189], v[52:55]
	v_mfma_f32_16x16x32_bf16 v[44:47], v[154:157], v[194:197], v[44:47]
	v_mfma_f32_16x16x32_bf16 v[36:39], v[162:165], v[194:197], v[36:39]
	v_mfma_f32_16x16x32_bf16 v[28:31], v[154:157], v[202:205], v[28:31]
	v_mfma_f32_16x16x32_bf16 v[20:23], v[162:165], v[202:205], v[20:23]
	v_mfma_f32_16x16x32_bf16 v[12:15], v[154:157], v[210:213], v[12:15]
	v_mfma_f32_16x16x32_bf16 v[4:7], v[162:165], v[210:213], v[4:7]
	v_mfma_f32_16x16x32_bf16 v[56:59], v[166:169], v[182:185], v[56:59]
	v_mfma_f32_16x16x32_bf16 v[48:51], v[174:177], v[182:185], v[48:51]
	v_mfma_f32_16x16x32_bf16 v[40:43], v[166:169], v[190:193], v[40:43]
	v_mfma_f32_16x16x32_bf16 v[32:35], v[174:177], v[190:193], v[32:35]
	v_mfma_f32_16x16x32_bf16 v[24:27], v[166:169], v[198:201], v[24:27]
	v_mfma_f32_16x16x32_bf16 v[16:19], v[174:177], v[198:201], v[16:19]
	v_mfma_f32_16x16x32_bf16 v[8:11], v[166:169], v[206:209], v[8:11]
	v_mfma_f32_16x16x32_bf16 v[0:3], v[174:177], v[206:209], v[0:3]
	v_mfma_f32_16x16x32_bf16 v[56:59], v[170:173], v[186:189], v[56:59]
	v_mfma_f32_16x16x32_bf16 v[48:51], v[178:181], v[186:189], v[48:51]
	v_mfma_f32_16x16x32_bf16 v[40:43], v[170:173], v[194:197], v[40:43]
	v_mfma_f32_16x16x32_bf16 v[32:35], v[178:181], v[194:197], v[32:35]
	v_mfma_f32_16x16x32_bf16 v[24:27], v[170:173], v[202:205], v[24:27]
	v_mfma_f32_16x16x32_bf16 v[16:19], v[178:181], v[202:205], v[16:19]
	v_mfma_f32_16x16x32_bf16 v[8:11], v[170:173], v[210:213], v[8:11]
	v_mfma_f32_16x16x32_bf16 v[0:3], v[178:181], v[210:213], v[0:3]
	s_setprio 0
	s_barrier
	s_add_i32 s53, s53, 2
	s_add_u32 s20, s20, 0x100
	s_addc_u32 s21, s21, 0
	s_add_u32 s51, s51, 0x100
	s_addc_u32 s52, s52, 0
	s_cmp_gt_u32 s53, 13
	s_cbranch_scc0 .LBB0_1704
	s_and_b64 vcc, exec, s[10:11]
	s_cbranch_vccz .LBB0_1707
	s_barrier

; #define PG8_STAGE(bufoff, gbase, voff) do { _Pragma("unroll") for (int _i = 0; _i < 2; ++_i) \
;         __builtin_amdgcn_global_load_lds((const unsigned*)((const char*)(gbase) + (voff)[_i]), (PG8_LAS unsigned*)(lds + (bufoff) + ldsw + _i * 8192), 16, 0, 0); } while (0)
; #define PG8_LDA(dst, b, h) do { _Pragma("unroll") for (int m = 0; m < 4; ++m) _Pragma("unroll") for (int k = 0; k < 2; ++k) dst[m][k] = *(const PG8_LAS bf16x8*)(lds + PG8_SA(b, h) + aoff + m * 2048 + k * 1024); } while (0)
; #define PG8_LDB(dst, b, h) do { _Pragma("unroll") for (int n = 0; n < 2; ++n) _Pragma("unroll") for (int k = 0; k < 2; ++k) dst[n][k] = *(const PG8_LAS bf16x8*)(lds + PG8_SB(b, h) + boff + n * 2048 + k * 1024); } while (0)
; #define PG8_MMA(ai, bj, At, Bt) do { __builtin_amdgcn_s_setprio(1); _Pragma("unroll") for (int m = 0; m < 4; ++m) _Pragma("unroll") for (int n = 0; n < 2; ++n) _Pragma("unroll") for (int k = 0; k < 2; ++k) \
;         acc[ai][bj][m][n] = __builtin_amdgcn_mfma_f32_16x16x32_bf16(Bt[n][k], At[m][k], acc[ai][bj][m][n], 0, 0, 0); __builtin_amdgcn_s_setprio(0); } while (0)
; #define PG8_WAIT_V(n) asm volatile("s_waitcnt vmcnt(" #n ")" ::: "memory")
; #define PG8_WAIT_L(n) asm volatile("s_waitcnt lgkmcnt(" #n ")" ::: "memory")
; #define PG8_BAR __builtin_amdgcn_s_barrier()
; #define PG8_SCHED __builtin_amdgcn_sched_barrier(0)
; template <class Epi, class Sched, bool ALIGN_EPI = false, bool SP2 = false>
; __device__ __forceinline__ void gemm_phase(PG8_LAS unsigned char* lds, const Gemm g, const Sched& S, const Epi& E, const int tid) {
;     ...
;             PG8_LDB(B0, 0, 0); PG8_LDB(B1, 0, 1); PG8_SCHED; PG8_LDA(At, 0, 0); PG8_STAGE(PG8_SA(1, 1), a1 + hstep, voffA);
;             PG8_WAIT_V(8); PG8_WAIT_L(0); PG8_BAR; PG8_MMA(0, 0, At, B0); PG8_MMA(0, 1, At, B1); PG8_BAR; PG8_SCHED;
;             PG8_LDA(At, 0, 1); PG8_STAGE(PG8_SB(0, 0), b2, voffB); PG8_STAGE(PG8_SB(0, 1), b2 + hstep, voffB); PG8_STAGE(PG8_SA(0, 0), a2, voffA);
;             PG8_WAIT_V(8); PG8_WAIT_L(0); PG8_BAR; PG8_MMA(1, 0, At, B0); PG8_MMA(1, 1, At, B1); PG8_BAR; PG8_SCHED;
.LBB0_1783:
	ds_read_b128 v[128:131], v180
	ds_read_b128 v[132:135], v180 offset:1024
	ds_read_b128 v[136:139], v180 offset:2048
	ds_read_b128 v[140:143], v180 offset:3072
	ds_read_b128 v[184:187], v181
	ds_read_b128 v[188:191], v181 offset:1024
	ds_read_b128 v[192:195], v181 offset:2048
	ds_read_b128 v[196:199], v181 offset:3072
	s_add_u32 s18, s16, 0x100
	s_addc_u32 s19, s17, 0
	s_cmp_eq_u32 s56, 40
	s_cselect_b32 s23, s3, s19
	s_cselect_b32 s22, s2, s18
	s_cselect_b32 s21, s15, s33
	s_cselect_b32 s20, s14, s25
	s_add_i32 m0, s37, 0xc000
	ds_read_b128 v[200:203], v182
	ds_read_b128 v[204:207], v182 offset:1024
	ds_read_b128 v[208:211], v182 offset:2048
	ds_read_b128 v[212:215], v182 offset:3072
	ds_read_b128 v[216:219], v182 offset:4096
	ds_read_b128 v[220:223], v182 offset:5120
	ds_read_b128 v[224:227], v182 offset:6144
	ds_read_b128 v[228:231], v182 offset:7168
	global_load_lds_dwordx4 v168, s[16:17]
	s_add_i32 m0, s37, 0xe000
	s_nop 0
	global_load_lds_dwordx4 v170, s[16:17]
	s_waitcnt vmcnt(8)
	s_waitcnt lgkmcnt(0)
	s_barrier
	s_setprio 1
	s_waitcnt lgkmcnt(0)
	v_mfma_f32_16x16x32_bf16 v[124:127], v[128:131], v[200:203], v[124:127]
	v_mfma_f32_16x16x32_bf16 v[120:123], v[136:139], v[200:203], v[120:123]
	v_mfma_f32_16x16x32_bf16 v[116:119], v[128:131], v[208:211], v[116:119]
	v_mfma_f32_16x16x32_bf16 v[104:107], v[136:139], v[208:211], v[104:107]
	v_mfma_f32_16x16x32_bf16 v[100:103], v[128:131], v[216:219], v[100:103]
	v_mfma_f32_16x16x32_bf16 v[88:91], v[136:139], v[216:219], v[88:91]
	v_mfma_f32_16x16x32_bf16 v[84:87], v[128:131], v[224:227], v[84:87]
	v_mfma_f32_16x16x32_bf16 v[72:75], v[136:139], v[224:227], v[72:75]
	v_mfma_f32_16x16x32_bf16 v[124:127], v[132:135], v[204:207], v[124:127]
	v_mfma_f32_16x16x32_bf16 v[120:123], v[140:143], v[204:207], v[120:123]
	v_mfma_f32_16x16x32_bf16 v[116:119], v[132:135], v[212:215], v[116:119]
	v_mfma_f32_16x16x32_bf16 v[104:107], v[140:143], v[212:215], v[104:107]
	v_mfma_f32_16x16x32_bf16 v[100:103], v[132:135], v[220:223], v[100:103]
	v_mfma_f32_16x16x32_bf16 v[88:91], v[140:143], v[220:223], v[88:91]
	v_mfma_f32_16x16x32_bf16 v[84:87], v[132:135], v[228:231], v[84:87]
	v_mfma_f32_16x16x32_bf16 v[72:75], v[140:143], v[228:231], v[72:75]
	v_mfma_f32_16x16x32_bf16 v[112:115], v[184:187], v[200:203], v[112:115]
	v_mfma_f32_16x16x32_bf16 v[108:111], v[192:195], v[200:203], v[108:111]
	v_mfma_f32_16x16x32_bf16 v[96:99], v[184:187], v[208:211], v[96:99]
	v_mfma_f32_16x16x32_bf16 v[92:95], v[192:195], v[208:211], v[92:95]
	v_mfma_f32_16x16x32_bf16 v[80:83], v[184:187], v[216:219], v[80:83]
	v_mfma_f32_16x16x32_bf16 v[76:79], v[192:195], v[216:219], v[76:79]
	v_mfma_f32_16x16x32_bf16 v[68:71], v[184:187], v[224:227], v[68:71]
	v_mfma_f32_16x16x32_bf16 v[64:67], v[192:195], v[224:227], v[64:67]
	v_mfma_f32_16x16x32_bf16 v[112:115], v[188:191], v[204:207], v[112:115]
	v_mfma_f32_16x16x32_bf16 v[108:111], v[196:199], v[204:207], v[108:111]
	v_mfma_f32_16x16x32_bf16 v[96:99], v[188:191], v[212:215], v[96:99]
	v_mfma_f32_16x16x32_bf16 v[92:95], v[196:199], v[212:215], v[92:95]
	v_mfma_f32_16x16x32_bf16 v[80:83], v[188:191], v[220:223], v[80:83]
	v_mfma_f32_16x16x32_bf16 v[76:79], v[196:199], v[220:223], v[76:79]
	v_mfma_f32_16x16x32_bf16 v[68:71], v[188:191], v[228:231], v[68:71]
	v_mfma_f32_16x16x32_bf16 v[64:67], v[196:199], v[228:231], v[64:67]
	s_setprio 0
	s_barrier
	s_add_i32 s16, s51, s36
	v_lshl_add_u64 v[176:177], s[20:21], 0, v[146:147]
	s_mov_b32 m0, s16
	ds_read_b128 v[200:203], v182 offset:16384
	ds_read_b128 v[204:207], v182 offset:17408
	ds_read_b128 v[208:211], v182 offset:18432
	ds_read_b128 v[212:215], v182 offset:19456
	ds_read_b128 v[216:219], v182 offset:20480
	ds_read_b128 v[220:223], v182 offset:21504
	ds_read_b128 v[224:227], v182 offset:22528
	ds_read_b128 v[228:231], v182 offset:23552
	global_load_lds_dwordx4 v[176:177], off
	s_add_i32 m0, s16, 0x2000
	s_add_u32 s16, s20, 0xb0000
	v_lshl_add_u64 v[232:233], s[20:21], 0, v[150:151]
	s_addc_u32 s17, s21, 0
	s_add_i32 s57, s52, s36
	global_load_lds_dwordx4 v[232:233], off
	s_mov_b32 m0, s57
	v_lshl_add_u64 v[236:237], s[22:23], 0, v[148:149]
	global_load_lds_dwordx4 v146, s[16:17]
	s_add_i32 m0, s57, 0x2000
	s_nop 0
	global_load_lds_dwordx4 v150, s[16:17]
	v_lshl_add_u64 v[234:235], s[22:23], 0, v[144:145]
	s_mov_b32 m0, s37
	s_nop 0
	global_load_lds_dwordx4 v[234:235], off
	s_mov_b32 m0, s38
	s_nop 0
	global_load_lds_dwordx4 v[236:237], off
	s_waitcnt vmcnt(8)
	s_waitcnt lgkmcnt(0)
	s_barrier
	s_setprio 1
	s_waitcnt lgkmcnt(0)
	v_mfma_f32_16x16x32_bf16 v[60:63], v[128:131], v[200:203], v[60:63]
	v_mfma_f32_16x16x32_bf16 v[56:59], v[136:139], v[200:203], v[56:59]
	v_mfma_f32_16x16x32_bf16 v[52:55], v[128:131], v[208:211], v[52:55]
	v_mfma_f32_16x16x32_bf16 v[40:43], v[136:139], v[208:211], v[40:43]
	v_mfma_f32_16x16x32_bf16 v[36:39], v[128:131], v[216:219], v[36:39]
	v_mfma_f32_16x16x32_bf16 v[24:27], v[136:139], v[216:219], v[24:27]
	v_mfma_f32_16x16x32_bf16 v[20:23], v[128:131], v[224:227], v[20:23]
	v_mfma_f32_16x16x32_bf16 v[8:11], v[136:139], v[224:227], v[8:11]
	v_mfma_f32_16x16x32_bf16 v[60:63], v[132:135], v[204:207], v[60:63]
	v_mfma_f32_16x16x32_bf16 v[56:59], v[140:143], v[204:207], v[56:59]
	v_mfma_f32_16x16x32_bf16 v[52:55], v[132:135], v[212:215], v[52:55]
	v_mfma_f32_16x16x32_bf16 v[40:43], v[140:143], v[212:215], v[40:43]
	v_mfma_f32_16x16x32_bf16 v[36:39], v[132:135], v[220:223], v[36:39]
	v_mfma_f32_16x16x32_bf16 v[24:27], v[140:143], v[220:223], v[24:27]
	v_mfma_f32_16x16x32_bf16 v[20:23], v[132:135], v[228:231], v[20:23]
	v_mfma_f32_16x16x32_bf16 v[8:11], v[140:143], v[228:231], v[8:11]
	v_mfma_f32_16x16x32_bf16 v[48:51], v[184:187], v[200:203], v[48:51]
	v_mfma_f32_16x16x32_bf16 v[44:47], v[192:195], v[200:203], v[44:47]
	v_mfma_f32_16x16x32_bf16 v[32:35], v[184:187], v[208:211], v[32:35]
	v_mfma_f32_16x16x32_bf16 v[28:31], v[192:195], v[208:211], v[28:31]
	v_mfma_f32_16x16x32_bf16 v[16:19], v[184:187], v[216:219], v[16:19]
	v_mfma_f32_16x16x32_bf16 v[12:15], v[192:195], v[216:219], v[12:15]
	v_mfma_f32_16x16x32_bf16 v[4:7], v[184:187], v[224:227], v[4:7]
	v_mfma_f32_16x16x32_bf16 v[0:3], v[192:195], v[224:227], v[0:3]
	v_mfma_f32_16x16x32_bf16 v[48:51], v[188:191], v[204:207], v[48:51]
	v_mfma_f32_16x16x32_bf16 v[44:47], v[196:199], v[204:207], v[44:47]
	v_mfma_f32_16x16x32_bf16 v[32:35], v[188:191], v[212:215], v[32:35]
	v_mfma_f32_16x16x32_bf16 v[28:31], v[196:199], v[212:215], v[28:31]
	v_mfma_f32_16x16x32_bf16 v[16:19], v[188:191], v[220:223], v[16:19]
	v_mfma_f32_16x16x32_bf16 v[12:15], v[196:199], v[220:223], v[12:15]
	v_mfma_f32_16x16x32_bf16 v[4:7], v[188:191], v[228:231], v[4:7]
	v_mfma_f32_16x16x32_bf16 v[0:3], v[196:199], v[228:231], v[0:3]
	s_setprio 0
	s_barrier
; #define PG8_STAGE(bufoff, gbase, voff) do { _Pragma("unroll") for (int _i = 0; _i < 2; ++_i) \
;         __builtin_amdgcn_global_load_lds((const unsigned*)((const char*)(gbase) + (voff)[_i]), (PG8_LAS unsigned*)(lds + (bufoff) + ldsw + _i * 8192), 16, 0, 0); } while (0)
; #define PG8_LDA(dst, b, h) do { _Pragma("unroll") for (int m = 0; m < 4; ++m) _Pragma("unroll") for (int k = 0; k < 2; ++k) dst[m][k] = *(const PG8_LAS bf16x8*)(lds + PG8_SA(b, h) + aoff + m * 2048 + k * 1024); } while (0)
; #define PG8_LDB(dst, b, h) do { _Pragma("unroll") for (int n = 0; n < 2; ++n) _Pragma("unroll") for (int k = 0; k < 2; ++k) dst[n][k] = *(const PG8_LAS bf16x8*)(lds + PG8_SB(b, h) + boff + n * 2048 + k * 1024); } while (0)
; #define PG8_MMA(ai, bj, At, Bt) do { __builtin_amdgcn_s_setprio(1); _Pragma("unroll") for (int m = 0; m < 4; ++m) _Pragma("unroll") for (int n = 0; n < 2; ++n) _Pragma("unroll") for (int k = 0; k < 2; ++k) \
;         acc[ai][bj][m][n] = __builtin_amdgcn_mfma_f32_16x16x32_bf16(Bt[n][k], At[m][k], acc[ai][bj][m][n], 0, 0, 0); __builtin_amdgcn_s_setprio(0); } while (0)
; #define PG8_WAIT_V(n) asm volatile("s_waitcnt vmcnt(" #n ")" ::: "memory")
; #define PG8_WAIT_L(n) asm volatile("s_waitcnt lgkmcnt(" #n ")" ::: "memory")
; #define PG8_BAR __builtin_amdgcn_s_barrier()
; #define PG8_SCHED __builtin_amdgcn_sched_barrier(0)
; template <class Epi, class Sched, bool ALIGN_EPI = false, bool SP2 = false>
; __device__ __forceinline__ void gemm_phase(PG8_LAS unsigned char* lds, const Gemm g, const Sched& S, const Epi& E, const int tid) {
;     ...
;             PG8_LDB(B0, 1, 0); PG8_LDB(B1, 1, 1); PG8_SCHED; PG8_LDA(At, 1, 0); PG8_STAGE(PG8_SA(0, 1), a2 + hstep, voffA);
;             PG8_WAIT_V(8); PG8_WAIT_L(0); PG8_BAR; PG8_MMA(0, 0, At, B0); PG8_MMA(0, 1, At, B1); PG8_BAR; PG8_SCHED;
;             PG8_LDA(At, 1, 1); PG8_STAGE(PG8_SB(1, 0), b3, voffB); PG8_STAGE(PG8_SB(1, 1), b3 + hstep, voffB); PG8_STAGE(PG8_SA(1, 0), a3, voffA);
;             PG8_WAIT_V(8); PG8_WAIT_L(0); PG8_BAR; PG8_MMA(1, 0, At, B0); PG8_MMA(1, 1, At, B1); PG8_BAR; PG8_SCHED;
	s_add_i32 s57, 0, 0x18000
	s_add_i32 s58, 0, 0x1c000
	v_add_u32_e32 v140, s57, v178
	v_add_u32_e32 v183, s58, v178
	ds_read_b128 v[128:131], v140
	ds_read_b128 v[132:135], v140 offset:1024
	ds_read_b128 v[136:139], v140 offset:2048
	ds_read_b128 v[140:143], v140 offset:3072
	ds_read_b128 v[184:187], v183
	ds_read_b128 v[188:191], v183 offset:1024
	ds_read_b128 v[192:195], v183 offset:2048
	ds_read_b128 v[196:199], v183 offset:3072
	s_add_u32 s16, s22, 0xb0000
	s_addc_u32 s17, s23, 0
	s_mov_b32 m0, s39
	ds_read_b128 v[200:203], v182 offset:32768
	ds_read_b128 v[204:207], v182 offset:33792
	ds_read_b128 v[208:211], v182 offset:34816
	ds_read_b128 v[212:215], v182 offset:35840
	ds_read_b128 v[216:219], v182 offset:36864
	ds_read_b128 v[220:223], v182 offset:37888
	ds_read_b128 v[224:227], v182 offset:38912
	ds_read_b128 v[228:231], v182 offset:39936
	global_load_lds_dwordx4 v144, s[16:17]
	v_lshl_add_u64 v[238:239], s[16:17], 0, v[148:149]
	s_mov_b32 m0, s40
	s_nop 0
	global_load_lds_dwordx4 v[238:239], off
	s_waitcnt vmcnt(8)
	s_waitcnt lgkmcnt(0)
	s_barrier
	s_setprio 1
	s_waitcnt lgkmcnt(0)
	v_mfma_f32_16x16x32_bf16 v[124:127], v[128:131], v[200:203], v[124:127]
	v_mfma_f32_16x16x32_bf16 v[120:123], v[136:139], v[200:203], v[120:123]
	v_mfma_f32_16x16x32_bf16 v[116:119], v[128:131], v[208:211], v[116:119]
	v_mfma_f32_16x16x32_bf16 v[104:107], v[136:139], v[208:211], v[104:107]
	v_mfma_f32_16x16x32_bf16 v[100:103], v[128:131], v[216:219], v[100:103]
	v_mfma_f32_16x16x32_bf16 v[88:91], v[136:139], v[216:219], v[88:91]
	v_mfma_f32_16x16x32_bf16 v[84:87], v[128:131], v[224:227], v[84:87]
	v_mfma_f32_16x16x32_bf16 v[72:75], v[136:139], v[224:227], v[72:75]
	v_mfma_f32_16x16x32_bf16 v[124:127], v[132:135], v[204:207], v[124:127]
	v_mfma_f32_16x16x32_bf16 v[120:123], v[140:143], v[204:207], v[120:123]
	v_mfma_f32_16x16x32_bf16 v[116:119], v[132:135], v[212:215], v[116:119]
	v_mfma_f32_16x16x32_bf16 v[104:107], v[140:143], v[212:215], v[104:107]
	v_mfma_f32_16x16x32_bf16 v[100:103], v[132:135], v[220:223], v[100:103]
	v_mfma_f32_16x16x32_bf16 v[88:91], v[140:143], v[220:223], v[88:91]
	v_mfma_f32_16x16x32_bf16 v[84:87], v[132:135], v[228:231], v[84:87]
	v_mfma_f32_16x16x32_bf16 v[72:75], v[140:143], v[228:231], v[72:75]
	v_mfma_f32_16x16x32_bf16 v[112:115], v[184:187], v[200:203], v[112:115]
	v_mfma_f32_16x16x32_bf16 v[108:111], v[192:195], v[200:203], v[108:111]
	v_mfma_f32_16x16x32_bf16 v[96:99], v[184:187], v[208:211], v[96:99]
	v_mfma_f32_16x16x32_bf16 v[92:95], v[192:195], v[208:211], v[92:95]
	v_mfma_f32_16x16x32_bf16 v[80:83], v[184:187], v[216:219], v[80:83]
	v_mfma_f32_16x16x32_bf16 v[76:79], v[192:195], v[216:219], v[76:79]
	v_mfma_f32_16x16x32_bf16 v[68:71], v[184:187], v[224:227], v[68:71]
	v_mfma_f32_16x16x32_bf16 v[64:67], v[192:195], v[224:227], v[64:67]
	v_mfma_f32_16x16x32_bf16 v[112:115], v[188:191], v[204:207], v[112:115]
	v_mfma_f32_16x16x32_bf16 v[108:111], v[196:199], v[204:207], v[108:111]
	v_mfma_f32_16x16x32_bf16 v[96:99], v[188:191], v[212:215], v[96:99]
	v_mfma_f32_16x16x32_bf16 v[92:95], v[196:199], v[212:215], v[92:95]
	v_mfma_f32_16x16x32_bf16 v[80:83], v[188:191], v[220:223], v[80:83]
	v_mfma_f32_16x16x32_bf16 v[76:79], v[196:199], v[220:223], v[76:79]
	v_mfma_f32_16x16x32_bf16 v[68:71], v[188:191], v[228:231], v[68:71]
	v_mfma_f32_16x16x32_bf16 v[64:67], v[196:199], v[228:231], v[64:67]
	s_setprio 0
	s_barrier
	s_add_i32 s16, s57, s36
	v_lshl_add_u64 v[176:177], v[176:177], 0, s[8:9]
	s_mov_b32 m0, s16
	ds_read_b128 v[200:203], v182 offset:49152
	ds_read_b128 v[204:207], v182 offset:50176
	ds_read_b128 v[208:211], v182 offset:51200
	ds_read_b128 v[212:215], v182 offset:52224
	ds_read_b128 v[216:219], v182 offset:53248
	ds_read_b128 v[220:223], v182 offset:54272
	ds_read_b128 v[224:227], v182 offset:55296
	ds_read_b128 v[228:231], v182 offset:56320
	global_load_lds_dwordx4 v[176:177], off
	s_add_i32 m0, s16, 0x2000
	s_add_u32 s16, s20, 0xb0080
	v_lshl_add_u64 v[176:177], v[232:233], 0, s[8:9]
	s_addc_u32 s17, s21, 0
	s_add_i32 s20, s58, s36
	global_load_lds_dwordx4 v[176:177], off
	s_mov_b32 m0, s20
	s_nop 0
	global_load_lds_dwordx4 v146, s[16:17]
	s_add_i32 m0, s20, 0x2000
	s_nop 0
	global_load_lds_dwordx4 v150, s[16:17]
	v_lshl_add_u64 v[176:177], v[234:235], 0, s[8:9]
	s_mov_b32 m0, s48
	s_nop 0
	global_load_lds_dwordx4 v[176:177], off
	v_lshl_add_u64 v[176:177], v[236:237], 0, s[8:9]
	s_mov_b32 m0, s49
	s_nop 0
	global_load_lds_dwordx4 v[176:177], off
	s_waitcnt vmcnt(8)
	s_waitcnt lgkmcnt(0)
	s_barrier
	s_setprio 1
	s_waitcnt lgkmcnt(0)
	v_mfma_f32_16x16x32_bf16 v[60:63], v[128:131], v[200:203], v[60:63]
	v_mfma_f32_16x16x32_bf16 v[56:59], v[136:139], v[200:203], v[56:59]
	v_mfma_f32_16x16x32_bf16 v[52:55], v[128:131], v[208:211], v[52:55]
	v_mfma_f32_16x16x32_bf16 v[40:43], v[136:139], v[208:211], v[40:43]
	v_mfma_f32_16x16x32_bf16 v[36:39], v[128:131], v[216:219], v[36:39]
	v_mfma_f32_16x16x32_bf16 v[24:27], v[136:139], v[216:219], v[24:27]
	v_mfma_f32_16x16x32_bf16 v[20:23], v[128:131], v[224:227], v[20:23]
	v_mfma_f32_16x16x32_bf16 v[8:11], v[136:139], v[224:227], v[8:11]
	v_mfma_f32_16x16x32_bf16 v[60:63], v[132:135], v[204:207], v[60:63]
	v_mfma_f32_16x16x32_bf16 v[56:59], v[140:143], v[204:207], v[56:59]
	v_mfma_f32_16x16x32_bf16 v[52:55], v[132:135], v[212:215], v[52:55]
	v_mfma_f32_16x16x32_bf16 v[40:43], v[140:143], v[212:215], v[40:43]
	v_mfma_f32_16x16x32_bf16 v[36:39], v[132:135], v[220:223], v[36:39]
	v_mfma_f32_16x16x32_bf16 v[24:27], v[140:143], v[220:223], v[24:27]
	v_mfma_f32_16x16x32_bf16 v[20:23], v[132:135], v[228:231], v[20:23]
	v_mfma_f32_16x16x32_bf16 v[8:11], v[140:143], v[228:231], v[8:11]
	v_mfma_f32_16x16x32_bf16 v[48:51], v[184:187], v[200:203], v[48:51]
	v_mfma_f32_16x16x32_bf16 v[44:47], v[192:195], v[200:203], v[44:47]
	v_mfma_f32_16x16x32_bf16 v[32:35], v[184:187], v[208:211], v[32:35]
	v_mfma_f32_16x16x32_bf16 v[28:31], v[192:195], v[208:211], v[28:31]
	v_mfma_f32_16x16x32_bf16 v[16:19], v[184:187], v[216:219], v[16:19]
	v_mfma_f32_16x16x32_bf16 v[12:15], v[192:195], v[216:219], v[12:15]
	v_mfma_f32_16x16x32_bf16 v[4:7], v[184:187], v[224:227], v[4:7]
	v_mfma_f32_16x16x32_bf16 v[0:3], v[192:195], v[224:227], v[0:3]
	v_mfma_f32_16x16x32_bf16 v[48:51], v[188:191], v[204:207], v[48:51]
	v_mfma_f32_16x16x32_bf16 v[44:47], v[196:199], v[204:207], v[44:47]
	v_mfma_f32_16x16x32_bf16 v[32:35], v[188:191], v[212:215], v[32:35]
	v_mfma_f32_16x16x32_bf16 v[28:31], v[196:199], v[212:215], v[28:31]
	v_mfma_f32_16x16x32_bf16 v[16:19], v[188:191], v[220:223], v[16:19]
	v_mfma_f32_16x16x32_bf16 v[12:15], v[196:199], v[220:223], v[12:15]
	v_mfma_f32_16x16x32_bf16 v[4:7], v[188:191], v[228:231], v[4:7]
	v_mfma_f32_16x16x32_bf16 v[0:3], v[196:199], v[228:231], v[0:3]
	s_setprio 0
	s_barrier
	s_add_i32 s56, s56, 2
	s_add_u32 s25, s25, 0x100
	s_addc_u32 s33, s33, 0
	s_cmp_gt_u32 s56, 41
	s_mov_b64 s[16:17], s[18:19]
	s_cbranch_scc0 .LBB0_1783
	s_and_b64 vcc, exec, s[10:11]
	s_cbranch_vccz .LBB0_1786
	s_barrier
